# MLA loop row-max reductions via v_permlane16/32_swap instead of ds_bpermute (on top of v28)
# baseline (speedup 1.0000x reference)
.LBB0_980:
	s_and_b32 s7, s6, 1
	s_mul_i32 s33, s7, 0x5800
	v_mov_b32_e32 v78, 0
	v_add_u32_e32 v138, s33, v123
	ds_read_b128 v[82:85], v138
	ds_read_b128 v[86:89], v138 offset:3328
	ds_read_b128 v[90:93], v138 offset:6656
	ds_read_b128 v[94:97], v138 offset:9984
	v_mov_b32_e32 v79, v78
	v_mov_b32_e32 v80, v78
	v_mov_b32_e32 v81, v78
	v_mov_b32_e32 v136, v153
	v_mov_b32_e32 v115, v113
	s_waitcnt lgkmcnt(0)
	v_mfma_f32_16x16x32_bf16 v[98:101], v[82:85], v[22:25], v[78:81]
	v_and_b32_e32 v148, 64, v170
	v_xor_b32_e32 v146, 16, v170
	v_add_u32_e32 v148, 64, v148
	v_mfma_f32_16x16x32_bf16 v[102:105], v[86:89], v[22:25], v[78:81]
	v_cmp_lt_i32_e32 vcc, v146, v148
	v_add_u32_e32 v140, 0xd00, v138
	v_add_u32_e32 v142, 0x1a00, v138
	v_mfma_f32_16x16x32_bf16 v[106:109], v[90:93], v[22:25], v[78:81]
	v_cndmask_b32_e32 v146, v170, v146, vcc
	v_lshlrev_b32_e32 v165, 2, v146
	v_add_u32_e32 v144, 0x2700, v138
	v_mfma_f32_16x16x32_bf16 v[152:155], v[94:97], v[22:25], v[78:81]
	s_xor_b32 s7, s7, 1
	s_mulk_i32 s7, 0x5800
	s_add_i32 s7, s92, s7
	v_mfma_f32_16x16x32_bf16 v[82:85], v[82:85], v[18:21], v[78:81]
	s_add_i32 s6, s6, 1
	v_mfma_f32_16x16x32_bf16 v[86:89], v[86:89], v[18:21], v[78:81]
	v_mfma_f32_16x16x32_bf16 v[90:93], v[90:93], v[18:21], v[78:81]
	v_mfma_f32_16x16x32_bf16 v[78:81], v[94:97], v[18:21], v[78:81]
	ds_read_b128 v[94:97], v138 offset:64
	ds_read_b128 v[166:169], v138 offset:3392
	ds_read_b128 v[172:175], v138 offset:6720
	ds_read_b128 v[176:179], v138 offset:10048
	s_waitcnt lgkmcnt(0)
	v_mfma_f32_16x16x32_bf16 v[98:101], v[94:97], v[14:17], v[98:101]
	v_mfma_f32_16x16x32_bf16 v[102:105], v[166:169], v[14:17], v[102:105]
	v_mfma_f32_16x16x32_bf16 v[180:183], v[172:175], v[14:17], v[106:109]
	v_mfma_f32_16x16x32_bf16 v[152:155], v[176:179], v[14:17], v[152:155]
	v_mfma_f32_16x16x32_bf16 v[86:89], v[166:169], v[10:13], v[86:89]
	v_mfma_f32_16x16x32_bf16 v[166:169], v[172:175], v[10:13], v[90:93]
	v_mfma_f32_16x16x32_bf16 v[78:81], v[176:179], v[10:13], v[78:81]
	s_nop 1
	ds_read_b128 v[90:93], v138 offset:128
	ds_read_b128 v[172:175], v138 offset:3456
	ds_read_b128 v[176:179], v138 offset:6784
	ds_read_b128 v[184:187], v138 offset:10112
	s_waitcnt lgkmcnt(0)
	v_mfma_f32_16x16x32_bf16 v[106:109], v[90:93], v[6:9], v[98:101]
	v_mfma_f32_16x16x32_bf16 v[102:105], v[172:175], v[6:9], v[102:105]
	v_mfma_f32_16x16x32_bf16 v[98:101], v[176:179], v[6:9], v[180:183]
	s_nop 5
	v_max3_f32 v113, v106, s70, v107
	v_max3_f32 v113, v113, v108, v109
	v_max3_f32 v113, v113, v102, v103
	v_mfma_f32_16x16x32_bf16 v[82:85], v[94:97], v[10:13], v[82:85]
	v_max3_f32 v113, v113, v104, v105
	v_max3_f32 v113, v113, v98, v99
	v_max3_f32 v113, v113, v100, v101
	v_mfma_f32_16x16x32_bf16 v[94:97], v[184:187], v[6:9], v[152:155]
	v_mfma_f32_16x16x32_bf16 v[90:93], v[90:93], v[2:5], v[82:85]
	v_mfma_f32_16x16x32_bf16 v[82:85], v[176:179], v[2:5], v[166:169]
	s_nop 5
	v_max3_f32 v113, v113, v94, v95
	v_max3_f32 v113, v113, v96, v97
	v_mov_b32_e32 v146, v113
	s_nop 1
	v_permlane16_swap_b32_e32 v146, v113
	v_mfma_f32_16x16x32_bf16 v[86:89], v[172:175], v[2:5], v[86:89]
	v_lshlrev_b32_e32 v167, 1, v112
	s_waitcnt lgkmcnt(0)
	v_max_f32_e32 v146, v146, v146
	v_max_f32_e32 v113, v113, v146
	v_xor_b32_e32 v146, 32, v170
	v_cmp_lt_i32_e32 vcc, v146, v148
	v_mfma_f32_16x16x32_bf16 v[78:81], v[184:187], v[2:5], v[78:81]
	s_nop 0
	v_cndmask_b32_e32 v146, v170, v146, vcc
	v_lshlrev_b32_e32 v166, 2, v146
	v_mov_b32_e32 v146, v113
	s_nop 1
	v_permlane32_swap_b32_e32 v146, v113
	v_cmp_eq_u32_e32 vcc, s6, v151
	s_or_b64 s[4:5], vcc, s[4:5]
	s_waitcnt lgkmcnt(0)
	v_max3_f32 v113, v115, v113, v146
	v_sub_f32_e32 v94, v94, v113
	v_exp_f32_e32 v200, v94
	v_sub_f32_e32 v94, v95, v113
	v_exp_f32_e32 v202, v94
	v_sub_f32_e32 v94, v96, v113
	v_exp_f32_e32 v204, v94
	v_sub_f32_e32 v94, v97, v113
	v_exp_f32_e32 v206, v94
	v_max3_f32 v94, v90, s70, v91
	v_max3_f32 v94, v94, v92, v93
	v_max3_f32 v94, v94, v86, v87
	v_max3_f32 v94, v94, v88, v89
	v_max3_f32 v94, v94, v82, v83
	v_max3_f32 v94, v94, v84, v85
	v_max3_f32 v94, v94, v78, v79
	v_max3_f32 v94, v94, v80, v81
	v_mov_b32_e32 v95, v94
	s_nop 1
	v_permlane16_swap_b32_e32 v95, v94
	v_sub_f32_e32 v102, v102, v113
	v_sub_f32_e32 v98, v98, v113
	v_exp_f32_e32 v184, v102
	v_sub_f32_e32 v102, v103, v113
	s_waitcnt lgkmcnt(0)
	v_max_f32_e32 v95, v95, v95
	v_max_f32_e32 v94, v94, v95
	v_mov_b32_e32 v95, v94
	s_nop 1
	v_permlane32_swap_b32_e32 v95, v94
	v_exp_f32_e32 v192, v98
	v_sub_f32_e32 v98, v99, v113
	v_exp_f32_e32 v186, v102
	v_sub_f32_e32 v102, v104, v113
	s_waitcnt lgkmcnt(0)
	v_max3_f32 v153, v136, v94, v95
	v_sub_f32_e32 v86, v86, v153
	v_sub_f32_e32 v82, v82, v153
	v_sub_f32_e32 v78, v78, v153
	v_exp_f32_e32 v194, v98
	v_sub_f32_e32 v98, v100, v113
	v_exp_f32_e32 v185, v86
	v_sub_f32_e32 v86, v87, v153
	v_exp_f32_e32 v193, v82
	v_sub_f32_e32 v82, v83, v153
	v_exp_f32_e32 v201, v78
	v_sub_f32_e32 v78, v79, v153
	v_exp_f32_e32 v188, v102
	v_sub_f32_e32 v102, v105, v113
	v_exp_f32_e32 v196, v98
	v_sub_f32_e32 v98, v101, v113
	v_sub_f32_e32 v94, v136, v153
	v_exp_f32_e32 v187, v86
	v_sub_f32_e32 v86, v88, v153
	v_exp_f32_e32 v195, v82
	v_sub_f32_e32 v82, v84, v153
	v_exp_f32_e32 v203, v78
	v_sub_f32_e32 v78, v80, v153
	v_exp_f32_e32 v190, v102
	v_exp_f32_e32 v198, v98
	v_exp_f32_e32 v189, v86
	v_sub_f32_e32 v86, v89, v153
	v_exp_f32_e32 v197, v82
	v_sub_f32_e32 v82, v85, v153
	v_exp_f32_e32 v205, v78
	v_sub_f32_e32 v78, v81, v153
	v_exp_f32_e32 v209, v94
	v_add_u32_e32 v94, v138, v125
	v_add_u32_e32 v98, v140, v137
	v_add_u32_e32 v102, v142, v139
	v_sub_f32_e32 v106, v106, v113
	v_exp_f32_e32 v191, v86
	v_exp_f32_e32 v199, v82
	v_exp_f32_e32 v207, v78
	ds_read_b128 v[78:81], v94 offset:13312
	ds_read_b128 v[82:85], v98 offset:13312
	ds_read_b128 v[86:89], v102 offset:13312
	v_exp_f32_e32 v154, v106
	v_sub_f32_e32 v106, v107, v113
	v_sub_f32_e32 v90, v90, v153
	v_exp_f32_e32 v168, v106
	v_sub_f32_e32 v106, v108, v113
	v_exp_f32_e32 v155, v90
	v_sub_f32_e32 v90, v91, v153
	v_sub_f32_e32 v115, v115, v113
	v_exp_f32_e32 v180, v106
	v_sub_f32_e32 v106, v109, v113
	v_exp_f32_e32 v169, v90
	v_exp_f32_e32 v182, v106
	v_exp_f32_e32 v208, v115
	v_sub_f32_e32 v90, v92, v153
	v_exp_f32_e32 v181, v90
	v_sub_f32_e32 v90, v93, v153
	v_exp_f32_e32 v183, v90
	v_add_u32_e32 v106, v144, v141
	v_cvt_pk_bf16_f32 v172, v154, v168
	v_cvt_pk_bf16_f32 v176, v155, v169
	v_pk_add_f32 v[154:155], v[154:155], 0 op_sel_hi:[1,0]
	ds_read_b128 v[90:93], v106 offset:13312
	ds_read_b128 v[94:97], v94 offset:13376
	ds_read_b128 v[98:101], v98 offset:13376
	ds_read_b128 v[102:105], v102 offset:13376
	ds_read_b128 v[106:109], v106 offset:13376
	v_cvt_pk_bf16_f32 v173, v180, v182
	v_cvt_pk_bf16_f32 v174, v184, v186
	v_pk_add_f32 v[154:155], v[168:169], v[154:155]
	v_pk_mul_f32 v[76:77], v[76:77], v[208:209] op_sel_hi:[1,0]
	v_pk_mul_f32 v[74:75], v[74:75], v[208:209] op_sel_hi:[1,0]
	v_pk_mul_f32 v[72:73], v[72:73], v[208:209] op_sel_hi:[1,0]
	v_pk_mul_f32 v[70:71], v[70:71], v[208:209] op_sel_hi:[1,0]
	v_pk_mul_f32 v[68:69], v[68:69], v[208:209] op_sel_hi:[1,0]
	v_pk_mul_f32 v[66:67], v[66:67], v[208:209] op_sel_hi:[1,0]
	v_pk_mul_f32 v[64:65], v[64:65], v[208:209] op_sel_hi:[1,0]
	v_pk_mul_f32 v[62:63], v[62:63], v[208:209] op_sel_hi:[1,0]
	v_cvt_pk_bf16_f32 v175, v188, v190
	v_pk_add_f32 v[154:155], v[180:181], v[154:155]
	v_mov_b32_e32 v136, v209
	s_waitcnt lgkmcnt(0)
	v_mfma_f32_16x16x32_bf16 v[74:77], v[78:81], v[172:175], v[74:77]
	v_add_f32_e64 v154, v182, v154
	v_add_f32_e64 v155, v183, v155
	v_cvt_pk_bf16_f32 v177, v181, v183
	v_cvt_pk_bf16_f32 v178, v185, v187
	v_mfma_f32_16x16x32_bf16 v[70:73], v[82:85], v[172:175], v[70:73]
	v_add_f32_e64 v154, v184, v154
	v_add_f32_e64 v155, v185, v155
	v_pk_mul_f32 v[40:41], v[40:41], v[136:137] op_sel_hi:[1,0]
	v_pk_mul_f32 v[38:39], v[38:39], v[136:137] op_sel_hi:[1,0]
	v_mfma_f32_16x16x32_bf16 v[66:69], v[86:89], v[172:175], v[66:69]
	v_cvt_pk_bf16_f32 v179, v189, v191
	v_pk_add_f32 v[154:155], v[186:187], v[154:155]
	v_lshlrev_b32_e32 v168, 1, v114
	v_mfma_f32_16x16x32_bf16 v[62:65], v[90:93], v[172:175], v[62:65]
	v_mul_f32_e64 v36, v36, v136
	v_mul_f32_e64 v37, v37, v136
	v_pk_mul_f32 v[34:35], v[34:35], v[136:137] op_sel_hi:[1,0]
	v_pk_mul_f32 v[32:33], v[32:33], v[136:137] op_sel_hi:[1,0]
	v_mfma_f32_16x16x32_bf16 v[38:41], v[78:81], v[176:179], v[38:41]
	v_cvt_pk_bf16_f32 v78, v192, v194
	v_cvt_pk_bf16_f32 v79, v196, v198
	v_cvt_pk_bf16_f32 v80, v200, v202
	v_cvt_pk_bf16_f32 v81, v204, v206
	v_pk_mul_f32 v[30:31], v[30:31], v[136:137] op_sel_hi:[1,0]
	v_pk_mul_f32 v[28:29], v[28:29], v[136:137] op_sel_hi:[1,0]
	v_mfma_f32_16x16x32_bf16 v[74:77], v[94:97], v[78:81], v[74:77]
	v_mul_f32_e64 v26, v26, v136
	v_mul_f32_e64 v27, v27, v136
	v_mfma_f32_16x16x32_bf16 v[70:73], v[98:101], v[78:81], v[70:73]
	v_mfma_f32_16x16x32_bf16 v[66:69], v[102:105], v[78:81], v[66:69]
	v_mfma_f32_16x16x32_bf16 v[62:65], v[106:109], v[78:81], v[62:65]
	v_add_f32_e64 v78, v188, v154
	v_add_f32_e64 v79, v189, v155
	v_lshlrev_b32_e32 v155, 1, v110
	v_pk_add_f32 v[78:79], v[190:191], v[78:79]
	v_mfma_f32_16x16x32_bf16 v[34:37], v[82:85], v[176:179], v[34:37]
	v_add_f32_e64 v78, v192, v78
	v_add_f32_e64 v79, v193, v79
	v_cvt_pk_bf16_f32 v82, v193, v195
	v_pk_add_f32 v[78:79], v[194:195], v[78:79]
	v_mfma_f32_16x16x32_bf16 v[30:33], v[86:89], v[176:179], v[30:33]
	v_add_f32_e64 v78, v196, v78
	v_add_f32_e64 v79, v197, v79
	v_cvt_pk_bf16_f32 v83, v197, v199
	v_pk_add_f32 v[78:79], v[198:199], v[78:79]
	v_mfma_f32_16x16x32_bf16 v[26:29], v[90:93], v[176:179], v[26:29]
	v_add_f32_e64 v78, v200, v78
	v_add_f32_e64 v79, v201, v79
	v_cvt_pk_bf16_f32 v84, v201, v203
	v_pk_add_f32 v[78:79], v[202:203], v[78:79]
	v_cvt_pk_bf16_f32 v85, v205, v207
	v_pk_add_f32 v[78:79], v[204:205], v[78:79]
	s_nop 0
	v_pk_add_f32 v[78:79], v[206:207], v[78:79]
	v_mfma_f32_16x16x32_bf16 v[38:41], v[94:97], v[82:85], v[38:41]
	v_fma_f32 v126, v126, v208, v78
	v_fma_f32 v127, v127, v209, v79
	v_add3_u32 v78, s7, v143, v155
	s_waitcnt vmcnt(0)
	ds_write_b128 v78, v[54:57]
	v_add3_u32 v54, s7, v145, v167
	ds_write_b128 v54, v[46:49]
	v_add3_u32 v46, s7, v147, v168
	ds_write_b128 v46, v[42:45]
	v_add3_u32 v42, s7, v149, v124
	ds_write_b128 v42, v[50:53] offset:13312
	ds_write_b128 v42, v[58:61] offset:17920
	v_lshl_add_u64 v[42:43], s[10:11], 0, v[134:135]
	v_lshl_add_u64 v[50:51], s[10:11], 0, v[128:129]
	global_load_dwordx4 v[54:57], v[42:43], off
	v_lshl_add_u64 v[58:59], s[10:11], 0, v[116:117]
	global_load_dwordx4 v[50:53], v[50:51], off
	v_lshl_add_u64 v[42:43], s[10:11], 0, v[132:133]
	global_load_dwordx4 v[46:49], v[42:43], off
	v_mfma_f32_16x16x32_bf16 v[34:37], v[98:101], v[82:85], v[34:37]
	global_load_dwordx4 v[58:61], v[58:59], off
	v_lshl_add_u64 v[42:43], s[10:11], 0, v[130:131]
	global_load_dwordx4 v[42:45], v[42:43], off
	v_mfma_f32_16x16x32_bf16 v[30:33], v[102:105], v[82:85], v[30:33]
	v_lshl_add_u64 v[116:117], v[116:117], 0, s[42:43]
	v_lshl_add_u64 v[128:129], v[128:129], 0, s[42:43]
	v_lshl_add_u64 v[130:131], v[130:131], 0, s[36:37]
	v_mfma_f32_16x16x32_bf16 v[26:29], v[106:109], v[82:85], v[26:29]
	v_lshl_add_u64 v[132:133], v[132:133], 0, s[36:37]
	v_lshl_add_u64 v[134:135], v[134:135], 0, s[36:37]
	s_waitcnt lgkmcnt(0)
	s_barrier
	s_andn2_b64 exec, exec, s[4:5]
	s_cbranch_execnz .LBB0_980
	s_or_b64 exec, exec, s[4:5]
	v_and_b32_e32 v78, 1, v151
	v_mov_b32_e32 v169, s92
	v_mad_u32_u24 v79, v78, s69, v169
	v_lshlrev_b32_e32 v80, 1, v118
	v_mov_b32_e32 v78, v1
	v_add3_u32 v171, v79, v80, v111
	ds_read_b128 v[82:85], v171
	ds_read_b128 v[86:89], v171 offset:64
	ds_read_b128 v[94:97], v171 offset:3328
	ds_read_b128 v[98:101], v171 offset:128
	v_mov_b32_e32 v79, v78
	v_mov_b32_e32 v80, v78
	v_mov_b32_e32 v81, v78
	ds_read_b128 v[106:109], v171 offset:6656
	ds_read_b128 v[114:117], v171 offset:6720
	s_waitcnt lgkmcnt(0)
	v_mfma_f32_16x16x32_bf16 v[90:93], v[82:85], v[22:25], v[78:81]
	ds_read_b128 v[132:135], v171 offset:9984
	ds_read_b128 v[172:175], v171 offset:6784
	ds_read_b128 v[180:183], v171 offset:3392
	ds_read_b128 v[184:187], v171 offset:3456
	ds_read_b128 v[188:191], v171 offset:10048
	ds_read_b128 v[192:195], v171 offset:10112
	v_mfma_f32_16x16x32_bf16 v[102:105], v[94:97], v[22:25], v[78:81]
	v_add_u32_e32 v200, 0x2700, v171
	v_ashrrev_i32_e32 v121, 31, v121
	v_mfma_f32_16x16x32_bf16 v[128:131], v[106:109], v[22:25], v[78:81]
	v_mfma_f32_16x16x32_bf16 v[90:93], v[86:89], v[14:17], v[90:93]
	s_waitcnt lgkmcnt(0)
	v_mfma_f32_16x16x32_bf16 v[176:179], v[132:135], v[22:25], v[78:81]
	v_mfma_f32_16x16x32_bf16 v[102:105], v[180:183], v[14:17], v[102:105]
	v_mfma_f32_16x16x32_bf16 v[128:131], v[114:117], v[14:17], v[128:131]
	v_mfma_f32_16x16x32_bf16 v[90:93], v[98:101], v[6:9], v[90:93]
	v_mfma_f32_16x16x32_bf16 v[176:179], v[188:191], v[14:17], v[176:179]
	v_mfma_f32_16x16x32_bf16 v[102:105], v[184:187], v[6:9], v[102:105]
	s_nop 5
	v_max3_f32 v110, v90, s70, v91
	v_max3_f32 v110, v110, v92, v93
	v_mfma_f32_16x16x32_bf16 v[196:199], v[172:175], v[6:9], v[128:131]
	v_mfma_f32_16x16x32_bf16 v[176:179], v[192:195], v[6:9], v[176:179]
	v_max3_f32 v110, v110, v102, v103
	v_max3_f32 v110, v110, v104, v105
	s_nop 4
	v_max3_f32 v110, v110, v196, v197
	v_max3_f32 v110, v110, v198, v199
	v_mfma_f32_16x16x32_bf16 v[82:85], v[82:85], v[18:21], v[78:81]
	v_max3_f32 v110, v110, v176, v177
	v_max3_f32 v110, v110, v178, v179
	ds_bpermute_b32 v111, v165, v110
	v_mfma_f32_16x16x32_bf16 v[94:97], v[94:97], v[18:21], v[78:81]
	v_add_u32_e32 v129, 0xd00, v171
	v_add_u32_e32 v131, 0x1a00, v171
	s_waitcnt lgkmcnt(0)
	v_max_f32_e32 v111, v111, v111
	v_max_f32_e32 v110, v110, v111
	ds_bpermute_b32 v111, v166, v110
	v_mfma_f32_16x16x32_bf16 v[106:109], v[106:109], v[18:21], v[78:81]
	s_waitcnt lgkmcnt(0)
	v_max3_f32 v228, v113, v110, v111
	v_sub_f32_e32 v90, v90, v228
	v_exp_f32_e32 v229, v90
	v_sub_f32_e32 v90, v91, v228
	v_exp_f32_e32 v230, v90
	v_sub_f32_e32 v90, v92, v228
	v_exp_f32_e32 v148, v90
	v_sub_f32_e32 v90, v93, v228
	v_mfma_f32_16x16x32_bf16 v[78:81], v[132:135], v[18:21], v[78:81]
	v_exp_f32_e32 v130, v90
	v_sub_f32_e32 v90, v102, v228
	v_exp_f32_e32 v134, v90
	v_mfma_f32_16x16x32_bf16 v[82:85], v[86:89], v[10:13], v[82:85]
	v_sub_f32_e32 v86, v104, v228
	v_sub_f32_e32 v90, v103, v228
	v_exp_f32_e32 v128, v86
	v_mfma_f32_16x16x32_bf16 v[86:89], v[180:183], v[10:13], v[94:97]
	v_exp_f32_e32 v138, v90
	v_sub_f32_e32 v90, v105, v228
	v_exp_f32_e32 v132, v90
	v_mfma_f32_16x16x32_bf16 v[90:93], v[114:117], v[10:13], v[106:109]
	v_sub_f32_e32 v110, v113, v228
	v_exp_f32_e32 v216, v110
	v_sub_f32_e32 v94, v196, v228
	v_mfma_f32_16x16x32_bf16 v[78:81], v[188:191], v[10:13], v[78:81]
	v_exp_f32_e32 v136, v94
	v_sub_f32_e32 v94, v197, v228
	v_exp_f32_e32 v140, v94
	v_mfma_f32_16x16x32_bf16 v[180:183], v[98:101], v[2:5], v[82:85]
	v_sub_f32_e32 v94, v198, v228
	v_exp_f32_e32 v142, v94
	v_sub_f32_e32 v94, v199, v228
	v_mfma_f32_16x16x32_bf16 v[184:187], v[184:187], v[2:5], v[86:89]
	v_sub_f32_e32 v82, v176, v228
	v_exp_f32_e32 v146, v82
	v_sub_f32_e32 v82, v177, v228
	v_mfma_f32_16x16x32_bf16 v[114:117], v[172:175], v[2:5], v[90:93]
	v_exp_f32_e32 v150, v82
	v_sub_f32_e32 v82, v178, v228
	v_exp_f32_e32 v152, v82
	v_mfma_f32_16x16x32_bf16 v[110:113], v[192:195], v[2:5], v[78:81]
	v_sub_f32_e32 v82, v179, v228
	v_exp_f32_e32 v144, v94
	v_exp_f32_e32 v154, v82
	v_max3_f32 v78, v180, s70, v181
	v_max3_f32 v78, v78, v182, v183
	v_max3_f32 v78, v78, v184, v185
	v_max3_f32 v78, v78, v186, v187
	v_add_u32_e32 v79, v129, v137
	v_bitop3_b32 v129, v151, 1, v151 bitop3:0xc
	v_max3_f32 v78, v78, v114, v115
	v_mad_u32_u24 v129, v129, s69, v169
	v_max3_f32 v133, v78, v116, v117
	v_add_u32_e32 v78, v171, v125
	v_add_u32_e32 v80, v131, v139
	v_add_u32_e32 v81, v200, v141
	v_add3_u32 v131, v129, v143, v155
	ds_read_b128 v[106:109], v78 offset:13312
	ds_read_b128 v[90:93], v78 offset:13376
	ds_read_b128 v[102:105], v79 offset:13312
	ds_read_b128 v[86:89], v79 offset:13376
	ds_read_b128 v[98:101], v80 offset:13312
	ds_read_b128 v[82:85], v80 offset:13376
	ds_read_b128 v[94:97], v81 offset:13312
	ds_read_b128 v[78:81], v81 offset:13376
	s_waitcnt vmcnt(0)
	ds_write_b128 v131, v[54:57]
	v_add3_u32 v54, v129, v145, v167
	ds_write_b128 v54, v[46:49]
	v_add3_u32 v46, v129, v147, v168
	ds_write_b128 v46, v[42:45]
	v_add3_u32 v42, v129, v149, v124
	ds_write_b128 v42, v[50:53] offset:13312
	ds_write_b128 v42, v[58:61] offset:17920
	v_max3_f32 v42, v133, v110, v111
	v_max3_f32 v42, v42, v112, v113
	ds_bpermute_b32 v43, v165, v42
	v_mov_b32_e32 v46, v1
	s_waitcnt lgkmcnt(0)
	s_barrier
	ds_read_b128 v[50:53], v123 offset:22528
	ds_read_b128 v[54:57], v123 offset:25856
	v_max_f32_e32 v43, v43, v43
	v_pk_mul_f32 v[44:45], v[68:69], v[216:217] op_sel_hi:[1,0]
	v_max_f32_e32 v68, v42, v43
	ds_bpermute_b32 v69, v166, v68
	ds_read_b128 v[58:61], v123 offset:29184
	ds_read_b128 v[172:175], v123 offset:22592
	ds_read_b128 v[188:191], v123 offset:32512
	ds_read_b128 v[192:195], v123 offset:22656
	ds_read_b128 v[200:203], v123 offset:29248
	ds_read_b128 v[224:227], v123 offset:25920
	v_mov_b32_e32 v47, v46
	v_mov_b32_e32 v48, v46
	v_mov_b32_e32 v49, v46
	v_mul_f32_e32 v126, v126, v216
	v_pk_mul_f32 v[76:77], v[76:77], v[216:217] op_sel_hi:[1,0]
	s_waitcnt lgkmcnt(8)
	v_mfma_f32_16x16x32_bf16 v[176:179], v[50:53], v[22:25], v[46:49]
	v_mul_f32_e64 v74, v74, v216
	v_mul_f32_e64 v75, v75, v216
	v_pk_mul_f32 v[72:73], v[72:73], v[216:217] op_sel_hi:[1,0]
	v_pk_mul_f32 v[70:71], v[70:71], v[216:217] op_sel_hi:[1,0]
	s_waitcnt lgkmcnt(7)
	v_mfma_f32_16x16x32_bf16 v[196:199], v[54:57], v[22:25], v[46:49]
	v_mul_f32_e64 v42, v66, v216
	v_mul_f32_e64 v43, v67, v216
	ds_read_b128 v[208:211], v123 offset:29312
	s_waitcnt lgkmcnt(6)
	v_mfma_f32_16x16x32_bf16 v[204:207], v[58:61], v[22:25], v[46:49]
	s_waitcnt lgkmcnt(4)
	v_mfma_f32_16x16x32_bf16 v[212:215], v[188:191], v[22:25], v[46:49]
	v_mul_f32_e64 v24, v64, v216
	v_mul_f32_e64 v25, v65, v216
	v_pk_mul_f32 v[22:23], v[62:63], v[216:217] op_sel_hi:[1,0]
	v_mfma_f32_16x16x32_bf16 v[62:65], v[50:53], v[18:21], v[46:49]
	v_max3_f32 v51, v153, v68, v69
	v_sub_f32_e32 v50, v180, v51
	v_sub_f32_e32 v52, v185, v51
	v_mfma_f32_16x16x32_bf16 v[216:219], v[54:57], v[18:21], v[46:49]
	v_exp_f32_e32 v55, v50
	v_sub_f32_e32 v50, v181, v51
	v_exp_f32_e32 v57, v50
	v_mfma_f32_16x16x32_bf16 v[220:223], v[58:61], v[18:21], v[46:49]
	v_sub_f32_e32 v50, v182, v51
	v_exp_f32_e32 v66, v52
	v_sub_f32_e32 v52, v186, v51
	v_mfma_f32_16x16x32_bf16 v[18:21], v[188:191], v[18:21], v[46:49]
	v_exp_f32_e32 v68, v52
	v_sub_f32_e32 v52, v187, v51
	v_sub_f32_e32 v53, v153, v51
	v_sub_f32_e32 v46, v183, v51
	v_exp_f32_e32 v54, v46
	v_sub_f32_e32 v46, v184, v51
	v_exp_f32_e32 v58, v46
	ds_read_b128 v[46:49], v123 offset:32576
	ds_read_b128 v[180:183], v123 offset:25984
	v_mfma_f32_16x16x32_bf16 v[176:179], v[172:175], v[14:17], v[176:179]
	ds_read_b128 v[184:187], v123 offset:32640
	v_exp_f32_e32 v50, v50
	v_exp_f32_e32 v52, v52
	s_waitcnt lgkmcnt(4)
	v_mfma_f32_16x16x32_bf16 v[188:191], v[224:227], v[14:17], v[196:199]
	v_mfma_f32_16x16x32_bf16 v[196:199], v[200:203], v[14:17], v[204:207]
	s_waitcnt lgkmcnt(2)
	v_mfma_f32_16x16x32_bf16 v[204:207], v[46:49], v[14:17], v[212:215]
	v_sub_f32_e32 v14, v114, v51
	v_exp_f32_e32 v56, v14
	v_sub_f32_e32 v14, v115, v51
	v_exp_f32_e32 v60, v14
	v_sub_f32_e32 v14, v116, v51
	v_mfma_f32_16x16x32_bf16 v[176:179], v[192:195], v[6:9], v[176:179]
	v_mfma_f32_16x16x32_bf16 v[172:175], v[172:175], v[10:13], v[62:65]
	s_nop 2
	v_exp_f32_e32 v62, v14
	v_sub_f32_e32 v14, v117, v51
	v_exp_f32_e32 v64, v14
	v_sub_f32_e32 v14, v110, v51
	s_waitcnt lgkmcnt(1)
	v_mfma_f32_16x16x32_bf16 v[188:191], v[180:183], v[6:9], v[188:191]
	v_exp_f32_e32 v110, v14
	v_sub_f32_e32 v14, v111, v51
	v_exp_f32_e32 v114, v14
	v_mfma_f32_16x16x32_bf16 v[212:215], v[224:227], v[10:13], v[216:219]
	v_mfma_f32_16x16x32_bf16 v[200:203], v[200:203], v[10:13], v[220:223]
	v_mfma_f32_16x16x32_bf16 v[16:19], v[46:49], v[10:13], v[18:21]
	v_sub_f32_e32 v10, v112, v51
	v_exp_f32_e32 v48, v10
	v_sub_f32_e32 v10, v113, v51
	v_mfma_f32_16x16x32_bf16 v[12:15], v[208:211], v[6:9], v[196:199]
	v_max3_f32 v21, v176, s70, v177
	v_max3_f32 v21, v21, v178, v179
	v_exp_f32_e32 v20, v10
	s_waitcnt lgkmcnt(0)
	v_mfma_f32_16x16x32_bf16 v[8:11], v[184:187], v[6:9], v[204:207]
	v_max3_f32 v21, v21, v188, v189
	v_max3_f32 v21, v21, v190, v191
	v_exp_f32_e32 v112, v53
	v_max3_f32 v21, v21, v12, v13
	v_max3_f32 v21, v21, v14, v15
	s_nop 2
	v_max3_f32 v21, v21, v8, v9
	v_max3_f32 v21, v21, v10, v11
	v_pk_mul_f32 v[196:197], v[30:31], v[112:113] op_sel_hi:[1,0]
	ds_bpermute_b32 v31, v165, v21
	v_add_f32_e32 v7, 0, v229
	v_mfma_f32_16x16x32_bf16 v[172:175], v[192:195], v[2:5], v[172:175]
	v_add_f32_e32 v30, v230, v7
	v_add_f32_e32 v7, 0, v55
	v_pk_mul_f32 v[198:199], v[32:33], v[112:113] op_sel_hi:[1,0]
	v_add_f32_e32 v32, v57, v7
	s_waitcnt lgkmcnt(0)
	v_max_f32_e32 v7, v31, v31
	v_mfma_f32_16x16x32_bf16 v[180:183], v[180:183], v[2:5], v[212:215]
	v_max_f32_e32 v7, v21, v7
	ds_bpermute_b32 v21, v166, v7
	v_pk_mul_f32 v[40:41], v[40:41], v[112:113] op_sel_hi:[1,0]
	v_mfma_f32_16x16x32_bf16 v[200:203], v[208:211], v[2:5], v[200:203]
	v_mul_f32_e64 v38, v38, v112
	v_mul_f32_e64 v39, v39, v112
	v_pk_mul_f32 v[36:37], v[36:37], v[112:113] op_sel_hi:[1,0]
	v_pk_mul_f32 v[34:35], v[34:35], v[112:113] op_sel_hi:[1,0]
	v_mfma_f32_16x16x32_bf16 v[2:5], v[184:187], v[2:5], v[16:19]
	v_mul_f32_e64 v28, v28, v112
	v_mul_f32_e64 v29, v29, v112
	v_pk_mul_f32 v[26:27], v[26:27], v[112:113] op_sel_hi:[1,0]
	s_waitcnt lgkmcnt(0)
	v_max3_f32 v113, v228, v7, v21
	v_max3_f32 v16, v172, s70, v173
	v_max3_f32 v16, v16, v174, v175
	v_max3_f32 v16, v16, v180, v181
	v_max3_f32 v16, v16, v182, v183
	v_max3_f32 v16, v16, v200, v201
	v_sub_f32_e32 v7, v176, v113
	v_max3_f32 v16, v16, v202, v203
	v_exp_f32_e32 v149, v7
	v_sub_f32_e32 v7, v177, v113
	v_max3_f32 v16, v16, v2, v3
	v_exp_f32_e32 v131, v7
	v_sub_f32_e32 v7, v178, v113
	v_max3_f32 v16, v16, v4, v5
	v_exp_f32_e32 v135, v7
	v_sub_f32_e32 v7, v179, v113
	ds_bpermute_b32 v17, v165, v16
	v_add_u32_e32 v33, v123, v139
	v_exp_f32_e32 v139, v7
	v_sub_f32_e32 v7, v188, v113
	v_exp_f32_e32 v129, v7
	v_sub_f32_e32 v7, v189, v113
	v_exp_f32_e32 v133, v7
	v_sub_f32_e32 v7, v190, v113
	v_add_u32_e32 v31, v123, v137
	v_exp_f32_e32 v137, v7
	v_sub_f32_e32 v7, v191, v113
	v_mul_f32_e32 v46, v127, v112
	v_add_u32_e32 v112, v123, v141
	v_exp_f32_e32 v141, v7
	v_sub_f32_e32 v7, v12, v113
	s_waitcnt lgkmcnt(0)
	v_max_f32_e32 v12, v17, v17
	v_max_f32_e32 v12, v16, v12
	ds_bpermute_b32 v16, v166, v12
	v_exp_f32_e32 v143, v7
	v_sub_f32_e32 v7, v13, v113
	v_exp_f32_e32 v145, v7
	v_sub_f32_e32 v7, v14, v113
	s_waitcnt lgkmcnt(0)
	v_max3_f32 v12, v51, v12, v16
	v_sub_f32_e32 v14, v172, v12
	v_sub_f32_e32 v13, v51, v12
	v_exp_f32_e32 v51, v14
	v_sub_f32_e32 v14, v173, v12
	v_cvt_pk_bf16_f32 v192, v55, v57
	v_exp_f32_e32 v55, v14
	v_sub_f32_e32 v14, v174, v12
	v_exp_f32_e32 v59, v14
	v_sub_f32_e32 v14, v175, v12
	v_exp_f32_e32 v67, v14
	v_sub_f32_e32 v14, v180, v12
	v_exp_f32_e32 v69, v14
	v_sub_f32_e32 v14, v181, v12
	v_exp_f32_e32 v53, v14
	v_sub_f32_e32 v14, v182, v12
	v_exp_f32_e32 v57, v14
	v_sub_f32_e32 v14, v183, v12
	v_exp_f32_e32 v61, v14
	v_sub_f32_e32 v14, v200, v12
	v_exp_f32_e32 v63, v14
	v_sub_f32_e32 v14, v201, v12
	v_sub_f32_e32 v2, v2, v12
	v_exp_f32_e32 v65, v14
	v_sub_f32_e32 v14, v202, v12
	v_exp_f32_e32 v49, v2
	v_sub_f32_e32 v2, v3, v12
	v_exp_f32_e32 v111, v14
	v_cvt_pk_bf16_f32 v193, v50, v54
	v_cvt_pk_bf16_f32 v194, v58, v66
	v_cvt_pk_bf16_f32 v195, v68, v52
	v_sub_f32_e32 v14, v203, v12
	v_exp_f32_e32 v21, v2
	v_sub_f32_e32 v2, v4, v12
	v_sub_f32_e32 v12, v5, v12
	v_mfma_f32_16x16x32_bf16 v[16:19], v[106:109], v[192:195], v[38:41]
	v_exp_f32_e32 v47, v2
	ds_read_b128 v[176:179], v31 offset:39168
	ds_read_b128 v[180:183], v33 offset:42496
	ds_read_b128 v[184:187], v112 offset:45824
	v_exp_f32_e32 v115, v14
	v_mfma_f32_16x16x32_bf16 v[36:39], v[102:105], v[192:195], v[34:37]
	v_exp_f32_e32 v147, v7
	v_sub_f32_e32 v7, v15, v113
	v_exp_f32_e32 v151, v7
	v_exp_f32_e32 v35, v12
	v_add_u32_e32 v12, v123, v125
	v_mfma_f32_16x16x32_bf16 v[172:175], v[98:101], v[192:195], v[196:199]
	v_exp_f32_e32 v34, v13
	v_sub_f32_e32 v7, v8, v113
	v_exp_f32_e32 v153, v7
	v_mfma_f32_16x16x32_bf16 v[2:5], v[94:97], v[192:195], v[26:29]
	ds_read_b128 v[188:191], v12 offset:35840
	ds_read_b128 v[192:195], v12 offset:35904
	ds_read_b128 v[200:203], v31 offset:39232
	ds_read_b128 v[204:207], v33 offset:42560
	v_mov_b32_e32 v33, v1
	v_pk_add_f32 v[32:33], v[50:51], v[32:33]
	v_cvt_pk_bf16_f32 v26, v56, v60
	v_pk_add_f32 v[32:33], v[54:55], v[32:33]
	v_cvt_pk_bf16_f32 v27, v62, v64
	v_pk_add_f32 v[32:33], v[58:59], v[32:33]
	v_cvt_pk_bf16_f32 v28, v110, v114
	v_pk_add_f32 v[32:33], v[66:67], v[32:33]
	v_cvt_pk_bf16_f32 v29, v48, v20
	v_pk_add_f32 v[32:33], v[68:69], v[32:33]
	v_sub_f32_e32 v7, v9, v113
	v_pk_add_f32 v[32:33], v[52:53], v[32:33]
	v_mfma_f32_16x16x32_bf16 v[36:39], v[86:89], v[26:29], v[36:39]
	v_add_f32_e64 v32, v56, v32
	v_add_f32_e64 v33, v57, v33
	v_cvt_pk_bf16_f32 v196, v51, v55
	v_pk_add_f32 v[32:33], v[60:61], v[32:33]
	v_mfma_f32_16x16x32_bf16 v[16:19], v[90:93], v[26:29], v[16:19]
	v_add_f32_e64 v32, v62, v32
	v_add_f32_e64 v33, v63, v33
	v_cvt_pk_bf16_f32 v197, v59, v67
	v_pk_add_f32 v[32:33], v[64:65], v[32:33]
	v_mfma_f32_16x16x32_bf16 v[172:175], v[82:85], v[26:29], v[172:175]
	v_cvt_pk_bf16_f32 v198, v69, v53
	v_cvt_pk_bf16_f32 v199, v57, v61
	v_exp_f32_e32 v155, v7
	v_mfma_f32_16x16x32_bf16 v[2:5], v[78:81], v[26:29], v[2:5]
	v_mul_f32_e64 v28, v38, v34
	v_mul_f32_e64 v29, v39, v34
	v_pk_mul_f32 v[26:27], v[36:37], v[34:35] op_sel_hi:[1,0]
	v_sub_f32_e32 v7, v10, v113
	v_pk_add_f32 v[32:33], v[110:111], v[32:33]
	v_cvt_pk_bf16_f32 v6, v229, v230
	v_pk_mul_f32 v[18:19], v[18:19], v[34:35] op_sel_hi:[1,0]
	v_pk_mul_f32 v[16:17], v[16:17], v[34:35] op_sel_hi:[1,0]
	s_waitcnt lgkmcnt(6)
	v_mfma_f32_16x16x32_bf16 v[36:39], v[176:179], v[196:199], v[26:29]
	v_mul_f32_e64 v4, v4, v34
	v_mul_f32_e64 v5, v5, v34
	v_pk_mul_f32 v[2:3], v[2:3], v[34:35] op_sel_hi:[1,0]
	v_exp_f32_e32 v127, v7
	v_pk_mul_f32 v[28:29], v[174:175], v[34:35] op_sel_hi:[1,0]
	v_pk_mul_f32 v[26:27], v[172:173], v[34:35] op_sel_hi:[1,0]
	v_cvt_pk_bf16_f32 v7, v148, v130
	v_cvt_pk_bf16_f32 v8, v134, v138
	v_cvt_pk_bf16_f32 v9, v128, v132
	v_pk_add_f32 v[32:33], v[114:115], v[32:33]
	v_mov_b32_e32 v31, v1
	s_waitcnt lgkmcnt(3)
	v_mfma_f32_16x16x32_bf16 v[16:19], v[188:191], v[196:199], v[16:19]
	v_sub_f32_e32 v10, v11, v113
	v_sub_f32_e32 v116, v228, v113
	v_exp_f32_e32 v11, v10
	v_mfma_f32_16x16x32_bf16 v[172:175], v[180:183], v[196:199], v[26:29]
	v_exp_f32_e32 v10, v116
	ds_read_b128 v[208:211], v112 offset:45888
	v_cvt_pk_bf16_f32 v54, v149, v131
	v_mfma_f32_16x16x32_bf16 v[2:5], v[184:187], v[196:199], v[2:5]
	v_cvt_pk_bf16_f32 v198, v49, v21
	v_cvt_pk_bf16_f32 v196, v63, v65
	v_cvt_pk_bf16_f32 v197, v111, v115
	v_mfma_f32_16x16x32_bf16 v[40:43], v[98:101], v[6:9], v[42:45]
	v_cvt_pk_bf16_f32 v199, v47, v35
	v_cvt_pk_bf16_f32 v55, v135, v139
	v_cvt_pk_bf16_f32 v56, v129, v133
	v_pk_add_f32 v[44:45], v[48:49], v[32:33]
	v_pk_add_f32 v[48:49], v[148:149], v[30:31]
	s_waitcnt lgkmcnt(3)
	v_mfma_f32_16x16x32_bf16 v[26:29], v[192:195], v[196:199], v[16:19]
	v_add_f32_e64 v48, v130, v48
	v_add_f32_e64 v49, v131, v49
	v_cvt_pk_bf16_f32 v33, v127, v11
	v_pk_add_f32 v[48:49], v[134:135], v[48:49]
	s_waitcnt lgkmcnt(2)
	v_mfma_f32_16x16x32_bf16 v[16:19], v[200:203], v[196:199], v[36:39]
	v_add_f32_e64 v48, v138, v48
	v_add_f32_e64 v49, v139, v49
	v_cvt_pk_bf16_f32 v57, v137, v141
	v_pk_add_f32 v[48:49], v[128:129], v[48:49]
	v_mfma_f32_16x16x32_bf16 v[36:39], v[106:109], v[6:9], v[74:77]
	v_add_f32_e64 v48, v132, v48
	v_add_f32_e64 v49, v133, v49
	v_cvt_pk_bf16_f32 v30, v143, v145
	v_pk_add_f32 v[48:49], v[136:137], v[48:49]
	v_mfma_f32_16x16x32_bf16 v[70:73], v[102:105], v[6:9], v[70:73]
	v_add_f32_e64 v48, v140, v48
	v_add_f32_e64 v49, v141, v49
	v_cvt_pk_bf16_f32 v31, v147, v151
	v_pk_add_f32 v[48:49], v[142:143], v[48:49]
	v_mfma_f32_16x16x32_bf16 v[6:9], v[94:97], v[6:9], v[22:25]
	v_add_f32_e64 v48, v144, v48
	v_add_f32_e64 v49, v145, v49
	v_cvt_pk_bf16_f32 v32, v153, v155
	v_pk_add_f32 v[48:49], v[146:147], v[48:49]
	v_cvt_pk_bf16_f32 v22, v136, v140
	v_pk_add_f32 v[48:49], v[150:151], v[48:49]
	v_cvt_pk_bf16_f32 v23, v142, v144
	v_pk_add_f32 v[48:49], v[152:153], v[48:49]
	v_cvt_pk_bf16_f32 v24, v146, v150
	v_pk_add_f32 v[48:49], v[154:155], v[48:49]
	v_cvt_pk_bf16_f32 v25, v152, v154
	v_pk_add_f32 v[48:49], v[126:127], v[48:49]
	s_waitcnt lgkmcnt(0)
	v_add_f32_e32 v49, v49, v11
	v_mfma_f32_16x16x32_bf16 v[36:39], v[90:93], v[22:25], v[36:39]
	v_fmac_f32_e32 v49, v48, v10
	ds_bpermute_b32 v48, v165, v49
	s_barrier
	v_mfma_f32_16x16x32_bf16 v[50:53], v[86:89], v[22:25], v[70:73]
	s_waitcnt lgkmcnt(0)
	v_mfma_f32_16x16x32_bf16 v[40:43], v[82:85], v[22:25], v[40:43]
	v_mfma_f32_16x16x32_bf16 v[6:9], v[78:81], v[22:25], v[6:9]
	s_nop 0
	v_mul_f32_e64 v24, v38, v10
	v_mul_f32_e64 v25, v39, v10
	v_pk_mul_f32 v[22:23], v[36:37], v[10:11] op_sel_hi:[1,0]
	s_nop 0
	v_pk_mul_f32 v[38:39], v[52:53], v[10:11] op_sel_hi:[1,0]
	v_pk_mul_f32 v[36:37], v[50:51], v[10:11] op_sel_hi:[1,0]
	v_pk_mul_f32 v[42:43], v[42:43], v[10:11] op_sel_hi:[1,0]
	v_pk_mul_f32 v[40:41], v[40:41], v[10:11] op_sel_hi:[1,0]
	v_pk_mul_f32 v[8:9], v[8:9], v[10:11] op_sel_hi:[1,0]
	v_pk_mul_f32 v[6:7], v[6:7], v[10:11] op_sel_hi:[1,0]
	v_pk_add_f32 v[10:11], v[20:21], v[44:45]
	v_mfma_f32_16x16x32_bf16 v[22:25], v[188:191], v[54:57], v[22:25]
	v_add_f32_e64 v10, v46, v10
	v_add_f32_e64 v11, v47, v11
	v_add_f32_e32 v21, v11, v35
	v_add_f32_e32 v11, v49, v48
	ds_bpermute_b32 v20, v166, v11
	v_mfma_f32_16x16x32_bf16 v[36:39], v[176:179], v[54:57], v[36:39]
	v_fmac_f32_e32 v21, v10, v34
	s_waitcnt lgkmcnt(0)
	v_add_f32_e32 v20, v11, v20
	v_mfma_f32_16x16x32_bf16 v[40:43], v[180:183], v[54:57], v[40:43]
	v_lshl_add_u64 v[10:11], v[120:121], 0, v[0:1]
	v_mfma_f32_16x16x32_bf16 v[6:9], v[184:187], v[54:57], v[6:9]
	v_mfma_f32_16x16x32_bf16 v[22:25], v[192:195], v[30:33], v[22:25]
	v_mfma_f32_16x16x32_bf16 v[36:39], v[200:203], v[30:33], v[36:39]
	v_mfma_f32_16x16x32_bf16 v[40:43], v[204:207], v[30:33], v[40:43]
	v_mfma_f32_16x16x32_bf16 v[6:9], v[208:211], v[30:33], v[6:9]
	v_div_scale_f32 v30, s[4:5], v20, v20, 1.0
	v_rcp_f32_e32 v31, v30
	v_mfma_f32_16x16x32_bf16 v[12:15], v[204:207], v[196:199], v[172:175]
	v_fma_f32 v0, -v30, v31, 1.0
	v_fmac_f32_e32 v31, v0, v31
	v_div_scale_f32 v0, vcc, 1.0, v20, 1.0
	v_mul_f32_e32 v32, v0, v31
	v_fma_f32 v33, -v30, v32, v0
	v_fmac_f32_e32 v32, v33, v31
	v_fma_f32 v0, -v30, v32, v0
	v_div_fmas_f32 v0, v0, v31, v32
	v_mov_b64_e32 v[30:31], s[10:11]
	v_mad_u64_u32 v[30:31], s[4:5], v10, s52, v[30:31]
	v_div_fixup_f32 v20, v0, v20, 1.0
	v_mad_i32_i24 v31, v11, s52, v31
	v_lshlrev_b32_e32 v0, 1, v119
	v_mov_b32_e32 v119, v1
	v_lshl_add_u64 v[10:11], v[30:31], 0, v[0:1]
	v_lshl_add_u64 v[10:11], v[10:11], 0, v[118:119]
	s_mov_b64 s[4:5], 0xa000c00
	ds_bpermute_b32 v0, v165, v21
	v_lshl_add_u64 v[30:31], v[10:11], 0, s[4:5]
	v_pk_mul_f32 v[22:23], v[22:23], v[20:21] op_sel_hi:[1,0]
	v_pk_mul_f32 v[24:25], v[24:25], v[20:21] op_sel_hi:[1,0]
	s_mov_b32 s4, 0xa000000
	v_cvt_pk_bf16_f32 v22, v22, v23
	v_cvt_pk_bf16_f32 v23, v24, v25
	v_add_co_u32_e32 v24, vcc, s4, v10
	s_waitcnt lgkmcnt(0)
	v_add_f32_e32 v0, v21, v0
	v_addc_co_u32_e32 v25, vcc, 0, v11, vcc
	global_store_dwordx2 v[24:25], v[22:23], off offset:3072
	v_pk_mul_f32 v[22:23], v[36:37], v[20:21] op_sel_hi:[1,0]
	v_pk_mul_f32 v[24:25], v[38:39], v[20:21] op_sel_hi:[1,0]
	v_cvt_pk_bf16_f32 v22, v22, v23
	v_cvt_pk_bf16_f32 v23, v24, v25
	global_store_dwordx2 v[30:31], v[22:23], off offset:32
	v_pk_mul_f32 v[22:23], v[40:41], v[20:21] op_sel_hi:[1,0]
	v_pk_mul_f32 v[24:25], v[42:43], v[20:21] op_sel_hi:[1,0]
	ds_bpermute_b32 v21, v166, v0
	v_mfma_f32_16x16x32_bf16 v[2:5], v[208:211], v[196:199], v[2:5]
	v_cvt_pk_bf16_f32 v22, v22, v23
	v_cvt_pk_bf16_f32 v23, v24, v25
	global_store_dwordx2 v[30:31], v[22:23], off offset:64
	s_waitcnt lgkmcnt(0)
	v_add_f32_e32 v0, v0, v21
	v_pk_mul_f32 v[6:7], v[6:7], v[20:21] op_sel_hi:[1,0]
	v_pk_mul_f32 v[8:9], v[8:9], v[20:21] op_sel_hi:[1,0]
	v_div_scale_f32 v20, s[4:5], v0, v0, 1.0
	v_rcp_f32_e32 v21, v20
	v_cvt_pk_bf16_f32 v6, v6, v7
	v_cvt_pk_bf16_f32 v7, v8, v9
	global_store_dwordx2 v[30:31], v[6:7], off offset:96
	v_fma_f32 v6, -v20, v21, 1.0
	v_fmac_f32_e32 v21, v6, v21
	v_div_scale_f32 v6, vcc, 1.0, v0, 1.0
	v_mul_f32_e32 v7, v6, v21
	v_fma_f32 v8, -v20, v7, v6
	v_fmac_f32_e32 v7, v8, v21
	v_fma_f32 v6, -v20, v7, v6
	v_div_fmas_f32 v6, v6, v21, v7
	s_mov_b64 s[4:5], 0xa01e000
	v_div_fixup_f32 v0, v6, v0, 1.0
	v_lshl_add_u64 v[6:7], v[10:11], 0, s[4:5]
	s_mov_b32 s4, 0xa01e000
	v_pk_mul_f32 v[8:9], v[26:27], v[0:1] op_sel_hi:[1,0]
	v_pk_mul_f32 v[20:21], v[28:29], v[0:1] op_sel_hi:[1,0]
	v_add_co_u32_e32 v10, vcc, s4, v10
	v_cvt_pk_bf16_f32 v8, v8, v9
	v_cvt_pk_bf16_f32 v9, v20, v21
	v_addc_co_u32_e32 v11, vcc, 0, v11, vcc
	global_store_dwordx2 v[10:11], v[8:9], off
	v_pk_mul_f32 v[8:9], v[16:17], v[0:1] op_sel_hi:[1,0]
	v_pk_mul_f32 v[10:11], v[18:19], v[0:1] op_sel_hi:[1,0]
	v_cvt_pk_bf16_f32 v8, v8, v9
	v_cvt_pk_bf16_f32 v9, v10, v11
	global_store_dwordx2 v[6:7], v[8:9], off offset:32
	v_pk_mul_f32 v[8:9], v[12:13], v[0:1] op_sel_hi:[1,0]
	v_pk_mul_f32 v[10:11], v[14:15], v[0:1] op_sel_hi:[1,0]
	v_pk_mul_f32 v[2:3], v[2:3], v[0:1] op_sel_hi:[1,0]
	v_pk_mul_f32 v[4:5], v[4:5], v[0:1] op_sel_hi:[1,0]
	v_cvt_pk_bf16_f32 v8, v8, v9
	v_cvt_pk_bf16_f32 v9, v10, v11
	v_cvt_pk_bf16_f32 v2, v2, v3
	v_cvt_pk_bf16_f32 v3, v4, v5
	global_store_dwordx2 v[6:7], v[8:9], off offset:64
	global_store_dwordx2 v[6:7], v[2:3], off offset:96

.LBB0_1975:
	s_and_b32 s5, s4, 1
	s_mul_i32 s8, s5, 0x5800
	v_mov_b32_e32 v78, 0
	v_add_u32_e32 v138, s8, v123
	ds_read_b128 v[82:85], v138
	ds_read_b128 v[86:89], v138 offset:3328
	ds_read_b128 v[90:93], v138 offset:6656
	ds_read_b128 v[94:97], v138 offset:9984
	v_mov_b32_e32 v79, v78
	v_mov_b32_e32 v80, v78
	v_mov_b32_e32 v81, v78
	v_mov_b32_e32 v136, v153
	v_mov_b32_e32 v115, v113
	s_waitcnt lgkmcnt(0)
	v_mfma_f32_16x16x32_bf16 v[98:101], v[82:85], v[22:25], v[78:81]
	v_and_b32_e32 v148, 64, v170
	v_xor_b32_e32 v146, 16, v170
	v_add_u32_e32 v148, 64, v148
	v_mfma_f32_16x16x32_bf16 v[102:105], v[86:89], v[22:25], v[78:81]
	v_cmp_lt_i32_e32 vcc, v146, v148
	v_add_u32_e32 v140, 0xd00, v138
	v_add_u32_e32 v142, 0x1a00, v138
	v_mfma_f32_16x16x32_bf16 v[106:109], v[90:93], v[22:25], v[78:81]
	v_cndmask_b32_e32 v146, v170, v146, vcc
	v_lshlrev_b32_e32 v165, 2, v146
	v_add_u32_e32 v144, 0x2700, v138
	v_mfma_f32_16x16x32_bf16 v[152:155], v[94:97], v[22:25], v[78:81]
	s_xor_b32 s5, s5, 1
	s_mulk_i32 s5, 0x5800
	s_add_i32 s5, s92, s5
	v_mfma_f32_16x16x32_bf16 v[82:85], v[82:85], v[18:21], v[78:81]
	s_add_i32 s4, s4, 1
	v_mfma_f32_16x16x32_bf16 v[86:89], v[86:89], v[18:21], v[78:81]
	v_mfma_f32_16x16x32_bf16 v[90:93], v[90:93], v[18:21], v[78:81]
	v_mfma_f32_16x16x32_bf16 v[78:81], v[94:97], v[18:21], v[78:81]
	ds_read_b128 v[94:97], v138 offset:64
	ds_read_b128 v[166:169], v138 offset:3392
	ds_read_b128 v[172:175], v138 offset:6720
	ds_read_b128 v[176:179], v138 offset:10048
	s_waitcnt lgkmcnt(0)
	v_mfma_f32_16x16x32_bf16 v[98:101], v[94:97], v[14:17], v[98:101]
	v_mfma_f32_16x16x32_bf16 v[102:105], v[166:169], v[14:17], v[102:105]
	v_mfma_f32_16x16x32_bf16 v[180:183], v[172:175], v[14:17], v[106:109]
	v_mfma_f32_16x16x32_bf16 v[152:155], v[176:179], v[14:17], v[152:155]
	v_mfma_f32_16x16x32_bf16 v[86:89], v[166:169], v[10:13], v[86:89]
	v_mfma_f32_16x16x32_bf16 v[166:169], v[172:175], v[10:13], v[90:93]
	v_mfma_f32_16x16x32_bf16 v[78:81], v[176:179], v[10:13], v[78:81]
	s_nop 1
	ds_read_b128 v[90:93], v138 offset:128
	ds_read_b128 v[172:175], v138 offset:3456
	ds_read_b128 v[176:179], v138 offset:6784
	ds_read_b128 v[184:187], v138 offset:10112
	s_waitcnt lgkmcnt(0)
	v_mfma_f32_16x16x32_bf16 v[106:109], v[90:93], v[6:9], v[98:101]
	v_mfma_f32_16x16x32_bf16 v[102:105], v[172:175], v[6:9], v[102:105]
	v_mfma_f32_16x16x32_bf16 v[98:101], v[176:179], v[6:9], v[180:183]
	s_nop 5
	v_max3_f32 v113, v106, s70, v107
	v_max3_f32 v113, v113, v108, v109
	v_max3_f32 v113, v113, v102, v103
	v_mfma_f32_16x16x32_bf16 v[82:85], v[94:97], v[10:13], v[82:85]
	v_max3_f32 v113, v113, v104, v105
	v_max3_f32 v113, v113, v98, v99
	v_max3_f32 v113, v113, v100, v101
	v_mfma_f32_16x16x32_bf16 v[94:97], v[184:187], v[6:9], v[152:155]
	v_mfma_f32_16x16x32_bf16 v[90:93], v[90:93], v[2:5], v[82:85]
	v_mfma_f32_16x16x32_bf16 v[82:85], v[176:179], v[2:5], v[166:169]
	s_nop 5
	v_max3_f32 v113, v113, v94, v95
	v_max3_f32 v113, v113, v96, v97
	v_mov_b32_e32 v146, v113
	s_nop 1
	v_permlane16_swap_b32_e32 v146, v113
	v_mfma_f32_16x16x32_bf16 v[86:89], v[172:175], v[2:5], v[86:89]
	v_lshlrev_b32_e32 v167, 1, v112
	s_waitcnt lgkmcnt(0)
	v_max_f32_e32 v146, v146, v146
	v_max_f32_e32 v113, v113, v146
	v_xor_b32_e32 v146, 32, v170
	v_cmp_lt_i32_e32 vcc, v146, v148
	v_mfma_f32_16x16x32_bf16 v[78:81], v[184:187], v[2:5], v[78:81]
	s_nop 0
	v_cndmask_b32_e32 v146, v170, v146, vcc
	v_lshlrev_b32_e32 v166, 2, v146
	v_mov_b32_e32 v146, v113
	s_nop 1
	v_permlane32_swap_b32_e32 v146, v113
	v_cmp_eq_u32_e32 vcc, s4, v151
	s_or_b64 s[2:3], vcc, s[2:3]
	s_waitcnt lgkmcnt(0)
	v_max3_f32 v113, v115, v113, v146
	v_sub_f32_e32 v94, v94, v113
	v_exp_f32_e32 v200, v94
	v_sub_f32_e32 v94, v95, v113
	v_exp_f32_e32 v202, v94
	v_sub_f32_e32 v94, v96, v113
	v_exp_f32_e32 v204, v94
	v_sub_f32_e32 v94, v97, v113
	v_exp_f32_e32 v206, v94
	v_max3_f32 v94, v90, s70, v91
	v_max3_f32 v94, v94, v92, v93
	v_max3_f32 v94, v94, v86, v87
	v_max3_f32 v94, v94, v88, v89
	v_max3_f32 v94, v94, v82, v83
	v_max3_f32 v94, v94, v84, v85
	v_max3_f32 v94, v94, v78, v79
	v_max3_f32 v94, v94, v80, v81
	v_mov_b32_e32 v95, v94
	s_nop 1
	v_permlane16_swap_b32_e32 v95, v94
	v_sub_f32_e32 v102, v102, v113
	v_sub_f32_e32 v98, v98, v113
	v_exp_f32_e32 v184, v102
	v_sub_f32_e32 v102, v103, v113
	s_waitcnt lgkmcnt(0)
	v_max_f32_e32 v95, v95, v95
	v_max_f32_e32 v94, v94, v95
	v_mov_b32_e32 v95, v94
	s_nop 1
	v_permlane32_swap_b32_e32 v95, v94
	v_exp_f32_e32 v192, v98
	v_sub_f32_e32 v98, v99, v113
	v_exp_f32_e32 v186, v102
	v_sub_f32_e32 v102, v104, v113
	s_waitcnt lgkmcnt(0)
	v_max3_f32 v153, v136, v94, v95
	v_sub_f32_e32 v86, v86, v153
	v_sub_f32_e32 v82, v82, v153
	v_sub_f32_e32 v78, v78, v153
	v_exp_f32_e32 v194, v98
	v_sub_f32_e32 v98, v100, v113
	v_exp_f32_e32 v185, v86
	v_sub_f32_e32 v86, v87, v153
	v_exp_f32_e32 v193, v82
	v_sub_f32_e32 v82, v83, v153
	v_exp_f32_e32 v201, v78
	v_sub_f32_e32 v78, v79, v153
	v_exp_f32_e32 v188, v102
	v_sub_f32_e32 v102, v105, v113
	v_exp_f32_e32 v196, v98
	v_sub_f32_e32 v98, v101, v113
	v_sub_f32_e32 v94, v136, v153
	v_exp_f32_e32 v187, v86
	v_sub_f32_e32 v86, v88, v153
	v_exp_f32_e32 v195, v82
	v_sub_f32_e32 v82, v84, v153
	v_exp_f32_e32 v203, v78
	v_sub_f32_e32 v78, v80, v153
	v_exp_f32_e32 v190, v102
	v_exp_f32_e32 v198, v98
	v_exp_f32_e32 v189, v86
	v_sub_f32_e32 v86, v89, v153
	v_exp_f32_e32 v197, v82
	v_sub_f32_e32 v82, v85, v153
	v_exp_f32_e32 v205, v78
	v_sub_f32_e32 v78, v81, v153
	v_exp_f32_e32 v209, v94
	v_add_u32_e32 v94, v138, v125
	v_add_u32_e32 v98, v140, v137
	v_add_u32_e32 v102, v142, v139
	v_sub_f32_e32 v106, v106, v113
	v_exp_f32_e32 v191, v86
	v_exp_f32_e32 v199, v82
	v_exp_f32_e32 v207, v78
	ds_read_b128 v[78:81], v94 offset:13312
	ds_read_b128 v[82:85], v98 offset:13312
	ds_read_b128 v[86:89], v102 offset:13312
	v_exp_f32_e32 v154, v106
	v_sub_f32_e32 v106, v107, v113
	v_sub_f32_e32 v90, v90, v153
	v_exp_f32_e32 v168, v106
	v_sub_f32_e32 v106, v108, v113
	v_exp_f32_e32 v155, v90
	v_sub_f32_e32 v90, v91, v153
	v_sub_f32_e32 v115, v115, v113
	v_exp_f32_e32 v180, v106
	v_sub_f32_e32 v106, v109, v113
	v_exp_f32_e32 v169, v90
	v_exp_f32_e32 v182, v106
	v_exp_f32_e32 v208, v115
	v_sub_f32_e32 v90, v92, v153
	v_exp_f32_e32 v181, v90
	v_sub_f32_e32 v90, v93, v153
	v_exp_f32_e32 v183, v90
	v_add_u32_e32 v106, v144, v141
	v_cvt_pk_bf16_f32 v172, v154, v168
	v_cvt_pk_bf16_f32 v176, v155, v169
	v_pk_add_f32 v[154:155], v[154:155], 0 op_sel_hi:[1,0]
	ds_read_b128 v[90:93], v106 offset:13312
	ds_read_b128 v[94:97], v94 offset:13376
	ds_read_b128 v[98:101], v98 offset:13376
	ds_read_b128 v[102:105], v102 offset:13376
	ds_read_b128 v[106:109], v106 offset:13376
	v_cvt_pk_bf16_f32 v173, v180, v182
	v_cvt_pk_bf16_f32 v174, v184, v186
	v_pk_add_f32 v[154:155], v[168:169], v[154:155]
	v_pk_mul_f32 v[76:77], v[76:77], v[208:209] op_sel_hi:[1,0]
	v_pk_mul_f32 v[74:75], v[74:75], v[208:209] op_sel_hi:[1,0]
	v_pk_mul_f32 v[72:73], v[72:73], v[208:209] op_sel_hi:[1,0]
	v_pk_mul_f32 v[70:71], v[70:71], v[208:209] op_sel_hi:[1,0]
	v_pk_mul_f32 v[68:69], v[68:69], v[208:209] op_sel_hi:[1,0]
	v_pk_mul_f32 v[66:67], v[66:67], v[208:209] op_sel_hi:[1,0]
	v_pk_mul_f32 v[64:65], v[64:65], v[208:209] op_sel_hi:[1,0]
	v_pk_mul_f32 v[62:63], v[62:63], v[208:209] op_sel_hi:[1,0]
	v_cvt_pk_bf16_f32 v175, v188, v190
	v_pk_add_f32 v[154:155], v[180:181], v[154:155]
	v_mov_b32_e32 v136, v209
	s_waitcnt lgkmcnt(0)
	v_mfma_f32_16x16x32_bf16 v[74:77], v[78:81], v[172:175], v[74:77]
	v_add_f32_e64 v154, v182, v154
	v_add_f32_e64 v155, v183, v155
	v_cvt_pk_bf16_f32 v177, v181, v183
	v_cvt_pk_bf16_f32 v178, v185, v187
	v_mfma_f32_16x16x32_bf16 v[70:73], v[82:85], v[172:175], v[70:73]
	v_add_f32_e64 v154, v184, v154
	v_add_f32_e64 v155, v185, v155
	v_pk_mul_f32 v[40:41], v[40:41], v[136:137] op_sel_hi:[1,0]
	v_pk_mul_f32 v[38:39], v[38:39], v[136:137] op_sel_hi:[1,0]
	v_mfma_f32_16x16x32_bf16 v[66:69], v[86:89], v[172:175], v[66:69]
	v_cvt_pk_bf16_f32 v179, v189, v191
	v_pk_add_f32 v[154:155], v[186:187], v[154:155]
	v_lshlrev_b32_e32 v168, 1, v114
	v_mfma_f32_16x16x32_bf16 v[62:65], v[90:93], v[172:175], v[62:65]
	v_mul_f32_e64 v36, v36, v136
	v_mul_f32_e64 v37, v37, v136
	v_pk_mul_f32 v[34:35], v[34:35], v[136:137] op_sel_hi:[1,0]
	v_pk_mul_f32 v[32:33], v[32:33], v[136:137] op_sel_hi:[1,0]
	v_mfma_f32_16x16x32_bf16 v[38:41], v[78:81], v[176:179], v[38:41]
	v_cvt_pk_bf16_f32 v78, v192, v194
	v_cvt_pk_bf16_f32 v79, v196, v198
	v_cvt_pk_bf16_f32 v80, v200, v202
	v_cvt_pk_bf16_f32 v81, v204, v206
	v_pk_mul_f32 v[30:31], v[30:31], v[136:137] op_sel_hi:[1,0]
	v_pk_mul_f32 v[28:29], v[28:29], v[136:137] op_sel_hi:[1,0]
	v_mfma_f32_16x16x32_bf16 v[74:77], v[94:97], v[78:81], v[74:77]
	v_mul_f32_e64 v26, v26, v136
	v_mul_f32_e64 v27, v27, v136
	v_mfma_f32_16x16x32_bf16 v[70:73], v[98:101], v[78:81], v[70:73]
	v_mfma_f32_16x16x32_bf16 v[66:69], v[102:105], v[78:81], v[66:69]
	v_mfma_f32_16x16x32_bf16 v[62:65], v[106:109], v[78:81], v[62:65]
	v_add_f32_e64 v78, v188, v154
	v_add_f32_e64 v79, v189, v155
	v_lshlrev_b32_e32 v155, 1, v110
	v_pk_add_f32 v[78:79], v[190:191], v[78:79]
	v_mfma_f32_16x16x32_bf16 v[34:37], v[82:85], v[176:179], v[34:37]
	v_add_f32_e64 v78, v192, v78
	v_add_f32_e64 v79, v193, v79
	v_cvt_pk_bf16_f32 v82, v193, v195
	v_pk_add_f32 v[78:79], v[194:195], v[78:79]
	v_mfma_f32_16x16x32_bf16 v[30:33], v[86:89], v[176:179], v[30:33]
	v_add_f32_e64 v78, v196, v78
	v_add_f32_e64 v79, v197, v79
	v_cvt_pk_bf16_f32 v83, v197, v199
	v_pk_add_f32 v[78:79], v[198:199], v[78:79]
	v_mfma_f32_16x16x32_bf16 v[26:29], v[90:93], v[176:179], v[26:29]
	v_add_f32_e64 v78, v200, v78
	v_add_f32_e64 v79, v201, v79
	v_cvt_pk_bf16_f32 v84, v201, v203
	v_pk_add_f32 v[78:79], v[202:203], v[78:79]
	v_cvt_pk_bf16_f32 v85, v205, v207
	v_pk_add_f32 v[78:79], v[204:205], v[78:79]
	s_nop 0
	v_pk_add_f32 v[78:79], v[206:207], v[78:79]
	v_mfma_f32_16x16x32_bf16 v[38:41], v[94:97], v[82:85], v[38:41]
	v_fma_f32 v126, v126, v208, v78
	v_fma_f32 v127, v127, v209, v79
	v_add3_u32 v78, s5, v143, v155
	s_waitcnt vmcnt(0)
	ds_write_b128 v78, v[54:57]
	v_add3_u32 v54, s5, v145, v167
	ds_write_b128 v54, v[46:49]
	v_add3_u32 v46, s5, v147, v168
	ds_write_b128 v46, v[42:45]
	v_add3_u32 v42, s5, v149, v124
	ds_write_b128 v42, v[50:53] offset:13312
	ds_write_b128 v42, v[58:61] offset:17920
	v_lshl_add_u64 v[42:43], s[12:13], 0, v[134:135]
	v_lshl_add_u64 v[50:51], s[12:13], 0, v[128:129]
	global_load_dwordx4 v[54:57], v[42:43], off
	v_lshl_add_u64 v[58:59], s[12:13], 0, v[116:117]
	global_load_dwordx4 v[50:53], v[50:51], off
	v_lshl_add_u64 v[42:43], s[12:13], 0, v[132:133]
	global_load_dwordx4 v[46:49], v[42:43], off
	v_mfma_f32_16x16x32_bf16 v[34:37], v[98:101], v[82:85], v[34:37]
	global_load_dwordx4 v[58:61], v[58:59], off
	v_lshl_add_u64 v[42:43], s[12:13], 0, v[130:131]
	global_load_dwordx4 v[42:45], v[42:43], off
	v_mfma_f32_16x16x32_bf16 v[30:33], v[102:105], v[82:85], v[30:33]
	v_lshl_add_u64 v[116:117], v[116:117], 0, s[44:45]
	v_lshl_add_u64 v[128:129], v[128:129], 0, s[44:45]
	v_lshl_add_u64 v[130:131], v[130:131], 0, s[38:39]
	v_mfma_f32_16x16x32_bf16 v[26:29], v[106:109], v[82:85], v[26:29]
	v_lshl_add_u64 v[132:133], v[132:133], 0, s[38:39]
	v_lshl_add_u64 v[134:135], v[134:135], 0, s[38:39]
	s_waitcnt lgkmcnt(0)
	s_barrier
	s_andn2_b64 exec, exec, s[2:3]
	s_cbranch_execnz .LBB0_1975
	s_or_b64 exec, exec, s[2:3]
	v_and_b32_e32 v78, 1, v151
	v_mov_b32_e32 v169, s92
	v_mad_u32_u24 v79, v78, s69, v169
	v_lshlrev_b32_e32 v80, 1, v118
	v_mov_b32_e32 v78, v1
	v_add3_u32 v171, v79, v80, v111
	ds_read_b128 v[82:85], v171
	ds_read_b128 v[86:89], v171 offset:64
	ds_read_b128 v[94:97], v171 offset:3328
	ds_read_b128 v[98:101], v171 offset:128
	v_mov_b32_e32 v79, v78
	v_mov_b32_e32 v80, v78
	v_mov_b32_e32 v81, v78
	ds_read_b128 v[106:109], v171 offset:6656
	ds_read_b128 v[114:117], v171 offset:6720
	s_waitcnt lgkmcnt(0)
	v_mfma_f32_16x16x32_bf16 v[90:93], v[82:85], v[22:25], v[78:81]
	ds_read_b128 v[132:135], v171 offset:9984
	ds_read_b128 v[172:175], v171 offset:6784
	ds_read_b128 v[180:183], v171 offset:3392
	ds_read_b128 v[184:187], v171 offset:3456
	ds_read_b128 v[188:191], v171 offset:10048
	ds_read_b128 v[192:195], v171 offset:10112
	v_mfma_f32_16x16x32_bf16 v[102:105], v[94:97], v[22:25], v[78:81]
	v_add_u32_e32 v200, 0x2700, v171
	v_ashrrev_i32_e32 v121, 31, v121
	v_mfma_f32_16x16x32_bf16 v[128:131], v[106:109], v[22:25], v[78:81]
	v_mfma_f32_16x16x32_bf16 v[90:93], v[86:89], v[14:17], v[90:93]
	s_waitcnt lgkmcnt(0)
	v_mfma_f32_16x16x32_bf16 v[176:179], v[132:135], v[22:25], v[78:81]
	v_mfma_f32_16x16x32_bf16 v[102:105], v[180:183], v[14:17], v[102:105]
	v_mfma_f32_16x16x32_bf16 v[128:131], v[114:117], v[14:17], v[128:131]
	v_mfma_f32_16x16x32_bf16 v[90:93], v[98:101], v[6:9], v[90:93]
	v_mfma_f32_16x16x32_bf16 v[176:179], v[188:191], v[14:17], v[176:179]
	v_mfma_f32_16x16x32_bf16 v[102:105], v[184:187], v[6:9], v[102:105]
	s_nop 5
	v_max3_f32 v110, v90, s70, v91
	v_max3_f32 v110, v110, v92, v93
	v_mfma_f32_16x16x32_bf16 v[196:199], v[172:175], v[6:9], v[128:131]
	v_mfma_f32_16x16x32_bf16 v[176:179], v[192:195], v[6:9], v[176:179]
	v_max3_f32 v110, v110, v102, v103
	v_max3_f32 v110, v110, v104, v105
	s_nop 4
	v_max3_f32 v110, v110, v196, v197
	v_max3_f32 v110, v110, v198, v199
	v_mfma_f32_16x16x32_bf16 v[82:85], v[82:85], v[18:21], v[78:81]
	v_max3_f32 v110, v110, v176, v177
	v_max3_f32 v110, v110, v178, v179
	ds_bpermute_b32 v111, v165, v110
	v_mfma_f32_16x16x32_bf16 v[94:97], v[94:97], v[18:21], v[78:81]
	v_add_u32_e32 v129, 0xd00, v171
	v_add_u32_e32 v131, 0x1a00, v171
	s_waitcnt lgkmcnt(0)
	v_max_f32_e32 v111, v111, v111
	v_max_f32_e32 v110, v110, v111
	ds_bpermute_b32 v111, v166, v110
	v_mfma_f32_16x16x32_bf16 v[106:109], v[106:109], v[18:21], v[78:81]
	s_waitcnt lgkmcnt(0)
	v_max3_f32 v228, v113, v110, v111
	v_sub_f32_e32 v90, v90, v228
	v_exp_f32_e32 v229, v90
	v_sub_f32_e32 v90, v91, v228
	v_exp_f32_e32 v230, v90
	v_sub_f32_e32 v90, v92, v228
	v_exp_f32_e32 v148, v90
	v_sub_f32_e32 v90, v93, v228
	v_mfma_f32_16x16x32_bf16 v[78:81], v[132:135], v[18:21], v[78:81]
	v_exp_f32_e32 v130, v90
	v_sub_f32_e32 v90, v102, v228
	v_exp_f32_e32 v134, v90
	v_mfma_f32_16x16x32_bf16 v[82:85], v[86:89], v[10:13], v[82:85]
	v_sub_f32_e32 v86, v104, v228
	v_sub_f32_e32 v90, v103, v228
	v_exp_f32_e32 v128, v86
	v_mfma_f32_16x16x32_bf16 v[86:89], v[180:183], v[10:13], v[94:97]
	v_exp_f32_e32 v138, v90
	v_sub_f32_e32 v90, v105, v228
	v_exp_f32_e32 v132, v90
	v_mfma_f32_16x16x32_bf16 v[90:93], v[114:117], v[10:13], v[106:109]
	v_sub_f32_e32 v110, v113, v228
	v_exp_f32_e32 v216, v110
	v_sub_f32_e32 v94, v196, v228
	v_mfma_f32_16x16x32_bf16 v[78:81], v[188:191], v[10:13], v[78:81]
	v_exp_f32_e32 v136, v94
	v_sub_f32_e32 v94, v197, v228
	v_exp_f32_e32 v140, v94
	v_mfma_f32_16x16x32_bf16 v[180:183], v[98:101], v[2:5], v[82:85]
	v_sub_f32_e32 v94, v198, v228
	v_exp_f32_e32 v142, v94
	v_sub_f32_e32 v94, v199, v228
	v_mfma_f32_16x16x32_bf16 v[184:187], v[184:187], v[2:5], v[86:89]
	v_sub_f32_e32 v82, v176, v228
	v_exp_f32_e32 v146, v82
	v_sub_f32_e32 v82, v177, v228
	v_mfma_f32_16x16x32_bf16 v[114:117], v[172:175], v[2:5], v[90:93]
	v_exp_f32_e32 v150, v82
	v_sub_f32_e32 v82, v178, v228
	v_exp_f32_e32 v152, v82
	v_mfma_f32_16x16x32_bf16 v[110:113], v[192:195], v[2:5], v[78:81]
	v_sub_f32_e32 v82, v179, v228
	v_exp_f32_e32 v144, v94
	v_exp_f32_e32 v154, v82
	v_max3_f32 v78, v180, s70, v181
	v_max3_f32 v78, v78, v182, v183
	v_max3_f32 v78, v78, v184, v185
	v_max3_f32 v78, v78, v186, v187
	v_add_u32_e32 v79, v129, v137
	v_bitop3_b32 v129, v151, 1, v151 bitop3:0xc
	v_max3_f32 v78, v78, v114, v115
	v_mad_u32_u24 v129, v129, s69, v169
	v_max3_f32 v133, v78, v116, v117
	v_add_u32_e32 v78, v171, v125
	v_add_u32_e32 v80, v131, v139
	v_add_u32_e32 v81, v200, v141
	v_add3_u32 v131, v129, v143, v155
	ds_read_b128 v[106:109], v78 offset:13312
	ds_read_b128 v[90:93], v78 offset:13376
	ds_read_b128 v[102:105], v79 offset:13312
	ds_read_b128 v[86:89], v79 offset:13376
	ds_read_b128 v[98:101], v80 offset:13312
	ds_read_b128 v[82:85], v80 offset:13376
	ds_read_b128 v[94:97], v81 offset:13312
	ds_read_b128 v[78:81], v81 offset:13376
	s_waitcnt vmcnt(0)
	ds_write_b128 v131, v[54:57]
	v_add3_u32 v54, v129, v145, v167
	ds_write_b128 v54, v[46:49]
	v_add3_u32 v46, v129, v147, v168
	ds_write_b128 v46, v[42:45]
	v_add3_u32 v42, v129, v149, v124
	ds_write_b128 v42, v[50:53] offset:13312
	ds_write_b128 v42, v[58:61] offset:17920
	v_max3_f32 v42, v133, v110, v111
	v_max3_f32 v42, v42, v112, v113
	ds_bpermute_b32 v43, v165, v42
	v_mov_b32_e32 v46, v1
	s_waitcnt lgkmcnt(0)
	s_barrier
	ds_read_b128 v[50:53], v123 offset:22528
	ds_read_b128 v[54:57], v123 offset:25856
	v_max_f32_e32 v43, v43, v43
	v_pk_mul_f32 v[44:45], v[68:69], v[216:217] op_sel_hi:[1,0]
	v_max_f32_e32 v68, v42, v43
	ds_bpermute_b32 v69, v166, v68
	ds_read_b128 v[58:61], v123 offset:29184
	ds_read_b128 v[172:175], v123 offset:22592
	ds_read_b128 v[188:191], v123 offset:32512
	ds_read_b128 v[192:195], v123 offset:22656
	ds_read_b128 v[200:203], v123 offset:29248
	ds_read_b128 v[224:227], v123 offset:25920
	v_mov_b32_e32 v47, v46
	v_mov_b32_e32 v48, v46
	v_mov_b32_e32 v49, v46
	v_mul_f32_e32 v126, v126, v216
	v_pk_mul_f32 v[76:77], v[76:77], v[216:217] op_sel_hi:[1,0]
	s_waitcnt lgkmcnt(8)
	v_mfma_f32_16x16x32_bf16 v[176:179], v[50:53], v[22:25], v[46:49]
	v_mul_f32_e64 v74, v74, v216
	v_mul_f32_e64 v75, v75, v216
	v_pk_mul_f32 v[72:73], v[72:73], v[216:217] op_sel_hi:[1,0]
	v_pk_mul_f32 v[70:71], v[70:71], v[216:217] op_sel_hi:[1,0]
	s_waitcnt lgkmcnt(7)
	v_mfma_f32_16x16x32_bf16 v[196:199], v[54:57], v[22:25], v[46:49]
	v_mul_f32_e64 v42, v66, v216
	v_mul_f32_e64 v43, v67, v216
	ds_read_b128 v[208:211], v123 offset:29312
	s_waitcnt lgkmcnt(6)
	v_mfma_f32_16x16x32_bf16 v[204:207], v[58:61], v[22:25], v[46:49]
	s_waitcnt lgkmcnt(4)
	v_mfma_f32_16x16x32_bf16 v[212:215], v[188:191], v[22:25], v[46:49]
	v_mul_f32_e64 v24, v64, v216
	v_mul_f32_e64 v25, v65, v216
	v_pk_mul_f32 v[22:23], v[62:63], v[216:217] op_sel_hi:[1,0]
	v_mfma_f32_16x16x32_bf16 v[62:65], v[50:53], v[18:21], v[46:49]
	v_max3_f32 v51, v153, v68, v69
	v_sub_f32_e32 v50, v180, v51
	v_sub_f32_e32 v52, v185, v51
	v_mfma_f32_16x16x32_bf16 v[216:219], v[54:57], v[18:21], v[46:49]
	v_exp_f32_e32 v55, v50
	v_sub_f32_e32 v50, v181, v51
	v_exp_f32_e32 v57, v50
	v_mfma_f32_16x16x32_bf16 v[220:223], v[58:61], v[18:21], v[46:49]
	v_sub_f32_e32 v50, v182, v51
	v_exp_f32_e32 v66, v52
	v_sub_f32_e32 v52, v186, v51
	v_mfma_f32_16x16x32_bf16 v[18:21], v[188:191], v[18:21], v[46:49]
	v_exp_f32_e32 v68, v52
	v_sub_f32_e32 v52, v187, v51
	v_sub_f32_e32 v53, v153, v51
	v_sub_f32_e32 v46, v183, v51
	v_exp_f32_e32 v54, v46
	v_sub_f32_e32 v46, v184, v51
	v_exp_f32_e32 v58, v46
	ds_read_b128 v[46:49], v123 offset:32576
	ds_read_b128 v[180:183], v123 offset:25984
	v_mfma_f32_16x16x32_bf16 v[176:179], v[172:175], v[14:17], v[176:179]
	ds_read_b128 v[184:187], v123 offset:32640
	v_exp_f32_e32 v50, v50
	v_exp_f32_e32 v52, v52
	s_waitcnt lgkmcnt(4)
	v_mfma_f32_16x16x32_bf16 v[188:191], v[224:227], v[14:17], v[196:199]
	v_mfma_f32_16x16x32_bf16 v[196:199], v[200:203], v[14:17], v[204:207]
	s_waitcnt lgkmcnt(2)
	v_mfma_f32_16x16x32_bf16 v[204:207], v[46:49], v[14:17], v[212:215]
	v_sub_f32_e32 v14, v114, v51
	v_exp_f32_e32 v56, v14
	v_sub_f32_e32 v14, v115, v51
	v_exp_f32_e32 v60, v14
	v_sub_f32_e32 v14, v116, v51
	v_mfma_f32_16x16x32_bf16 v[176:179], v[192:195], v[6:9], v[176:179]
	v_mfma_f32_16x16x32_bf16 v[172:175], v[172:175], v[10:13], v[62:65]
	s_nop 2
	v_exp_f32_e32 v62, v14
	v_sub_f32_e32 v14, v117, v51
	v_exp_f32_e32 v64, v14
	v_sub_f32_e32 v14, v110, v51
	s_waitcnt lgkmcnt(1)
	v_mfma_f32_16x16x32_bf16 v[188:191], v[180:183], v[6:9], v[188:191]
	v_exp_f32_e32 v110, v14
	v_sub_f32_e32 v14, v111, v51
	v_exp_f32_e32 v114, v14
	v_mfma_f32_16x16x32_bf16 v[212:215], v[224:227], v[10:13], v[216:219]
	v_mfma_f32_16x16x32_bf16 v[200:203], v[200:203], v[10:13], v[220:223]
	v_mfma_f32_16x16x32_bf16 v[16:19], v[46:49], v[10:13], v[18:21]
	v_sub_f32_e32 v10, v112, v51
	v_exp_f32_e32 v48, v10
	v_sub_f32_e32 v10, v113, v51
	v_mfma_f32_16x16x32_bf16 v[12:15], v[208:211], v[6:9], v[196:199]
	v_max3_f32 v21, v176, s70, v177
	v_max3_f32 v21, v21, v178, v179
	v_exp_f32_e32 v20, v10
	s_waitcnt lgkmcnt(0)
	v_mfma_f32_16x16x32_bf16 v[8:11], v[184:187], v[6:9], v[204:207]
	v_max3_f32 v21, v21, v188, v189
	v_max3_f32 v21, v21, v190, v191
	v_exp_f32_e32 v112, v53
	v_max3_f32 v21, v21, v12, v13
	v_max3_f32 v21, v21, v14, v15
	s_nop 2
	v_max3_f32 v21, v21, v8, v9
	v_max3_f32 v21, v21, v10, v11
	v_pk_mul_f32 v[196:197], v[30:31], v[112:113] op_sel_hi:[1,0]
	ds_bpermute_b32 v31, v165, v21
	v_add_f32_e32 v7, 0, v229
	v_mfma_f32_16x16x32_bf16 v[172:175], v[192:195], v[2:5], v[172:175]
	v_add_f32_e32 v30, v230, v7
	v_add_f32_e32 v7, 0, v55
	v_pk_mul_f32 v[198:199], v[32:33], v[112:113] op_sel_hi:[1,0]
	v_add_f32_e32 v32, v57, v7
	s_waitcnt lgkmcnt(0)
	v_max_f32_e32 v7, v31, v31
	v_mfma_f32_16x16x32_bf16 v[180:183], v[180:183], v[2:5], v[212:215]
	v_max_f32_e32 v7, v21, v7
	ds_bpermute_b32 v21, v166, v7
	v_pk_mul_f32 v[40:41], v[40:41], v[112:113] op_sel_hi:[1,0]
	v_mfma_f32_16x16x32_bf16 v[200:203], v[208:211], v[2:5], v[200:203]
	v_mul_f32_e64 v38, v38, v112
	v_mul_f32_e64 v39, v39, v112
	v_pk_mul_f32 v[36:37], v[36:37], v[112:113] op_sel_hi:[1,0]
	v_pk_mul_f32 v[34:35], v[34:35], v[112:113] op_sel_hi:[1,0]
	v_mfma_f32_16x16x32_bf16 v[2:5], v[184:187], v[2:5], v[16:19]
	v_mul_f32_e64 v28, v28, v112
	v_mul_f32_e64 v29, v29, v112
	v_pk_mul_f32 v[26:27], v[26:27], v[112:113] op_sel_hi:[1,0]
	s_waitcnt lgkmcnt(0)
	v_max3_f32 v113, v228, v7, v21
	v_max3_f32 v16, v172, s70, v173
	v_max3_f32 v16, v16, v174, v175
	v_max3_f32 v16, v16, v180, v181
	v_max3_f32 v16, v16, v182, v183
	v_max3_f32 v16, v16, v200, v201
	v_sub_f32_e32 v7, v176, v113
	v_max3_f32 v16, v16, v202, v203
	v_exp_f32_e32 v149, v7
	v_sub_f32_e32 v7, v177, v113
	v_max3_f32 v16, v16, v2, v3
	v_exp_f32_e32 v131, v7
	v_sub_f32_e32 v7, v178, v113
	v_max3_f32 v16, v16, v4, v5
	v_exp_f32_e32 v135, v7
	v_sub_f32_e32 v7, v179, v113
	ds_bpermute_b32 v17, v165, v16
	v_add_u32_e32 v33, v123, v139
	v_exp_f32_e32 v139, v7
	v_sub_f32_e32 v7, v188, v113
	v_exp_f32_e32 v129, v7
	v_sub_f32_e32 v7, v189, v113
	v_exp_f32_e32 v133, v7
	v_sub_f32_e32 v7, v190, v113
	v_add_u32_e32 v31, v123, v137
	v_exp_f32_e32 v137, v7
	v_sub_f32_e32 v7, v191, v113
	v_mul_f32_e32 v46, v127, v112
	v_add_u32_e32 v112, v123, v141
	v_exp_f32_e32 v141, v7
	v_sub_f32_e32 v7, v12, v113
	s_waitcnt lgkmcnt(0)
	v_max_f32_e32 v12, v17, v17
	v_max_f32_e32 v12, v16, v12
	ds_bpermute_b32 v16, v166, v12
	v_exp_f32_e32 v143, v7
	v_sub_f32_e32 v7, v13, v113
	v_exp_f32_e32 v145, v7
	v_sub_f32_e32 v7, v14, v113
	s_waitcnt lgkmcnt(0)
	v_max3_f32 v12, v51, v12, v16
	v_sub_f32_e32 v14, v172, v12
	v_sub_f32_e32 v13, v51, v12
	v_exp_f32_e32 v51, v14
	v_sub_f32_e32 v14, v173, v12
	v_cvt_pk_bf16_f32 v192, v55, v57
	v_exp_f32_e32 v55, v14
	v_sub_f32_e32 v14, v174, v12
	v_exp_f32_e32 v59, v14
	v_sub_f32_e32 v14, v175, v12
	v_exp_f32_e32 v67, v14
	v_sub_f32_e32 v14, v180, v12
	v_exp_f32_e32 v69, v14
	v_sub_f32_e32 v14, v181, v12
	v_exp_f32_e32 v53, v14
	v_sub_f32_e32 v14, v182, v12
	v_exp_f32_e32 v57, v14
	v_sub_f32_e32 v14, v183, v12
	v_exp_f32_e32 v61, v14
	v_sub_f32_e32 v14, v200, v12
	v_exp_f32_e32 v63, v14
	v_sub_f32_e32 v14, v201, v12
	v_sub_f32_e32 v2, v2, v12
	v_exp_f32_e32 v65, v14
	v_sub_f32_e32 v14, v202, v12
	v_exp_f32_e32 v49, v2
	v_sub_f32_e32 v2, v3, v12
	v_exp_f32_e32 v111, v14
	v_cvt_pk_bf16_f32 v193, v50, v54
	v_cvt_pk_bf16_f32 v194, v58, v66
	v_cvt_pk_bf16_f32 v195, v68, v52
	v_sub_f32_e32 v14, v203, v12
	v_exp_f32_e32 v21, v2
	v_sub_f32_e32 v2, v4, v12
	v_sub_f32_e32 v12, v5, v12
	v_mfma_f32_16x16x32_bf16 v[16:19], v[106:109], v[192:195], v[38:41]
	v_exp_f32_e32 v47, v2
	ds_read_b128 v[176:179], v31 offset:39168
	ds_read_b128 v[180:183], v33 offset:42496
	ds_read_b128 v[184:187], v112 offset:45824
	v_exp_f32_e32 v115, v14
	v_mfma_f32_16x16x32_bf16 v[36:39], v[102:105], v[192:195], v[34:37]
	v_exp_f32_e32 v147, v7
	v_sub_f32_e32 v7, v15, v113
	v_exp_f32_e32 v151, v7
	v_exp_f32_e32 v35, v12
	v_add_u32_e32 v12, v123, v125
	v_mfma_f32_16x16x32_bf16 v[172:175], v[98:101], v[192:195], v[196:199]
	v_exp_f32_e32 v34, v13
	v_sub_f32_e32 v7, v8, v113
	v_exp_f32_e32 v153, v7
	v_mfma_f32_16x16x32_bf16 v[2:5], v[94:97], v[192:195], v[26:29]
	ds_read_b128 v[188:191], v12 offset:35840
	ds_read_b128 v[192:195], v12 offset:35904
	ds_read_b128 v[200:203], v31 offset:39232
	ds_read_b128 v[204:207], v33 offset:42560
	v_mov_b32_e32 v33, v1
	v_pk_add_f32 v[32:33], v[50:51], v[32:33]
	v_cvt_pk_bf16_f32 v26, v56, v60
	v_pk_add_f32 v[32:33], v[54:55], v[32:33]
	v_cvt_pk_bf16_f32 v27, v62, v64
	v_pk_add_f32 v[32:33], v[58:59], v[32:33]
	v_cvt_pk_bf16_f32 v28, v110, v114
	v_pk_add_f32 v[32:33], v[66:67], v[32:33]
	v_cvt_pk_bf16_f32 v29, v48, v20
	v_pk_add_f32 v[32:33], v[68:69], v[32:33]
	v_sub_f32_e32 v7, v9, v113
	v_pk_add_f32 v[32:33], v[52:53], v[32:33]
	v_mfma_f32_16x16x32_bf16 v[36:39], v[86:89], v[26:29], v[36:39]
	v_add_f32_e64 v32, v56, v32
	v_add_f32_e64 v33, v57, v33
	v_cvt_pk_bf16_f32 v196, v51, v55
	v_pk_add_f32 v[32:33], v[60:61], v[32:33]
	v_mfma_f32_16x16x32_bf16 v[16:19], v[90:93], v[26:29], v[16:19]
	v_add_f32_e64 v32, v62, v32
	v_add_f32_e64 v33, v63, v33
	v_cvt_pk_bf16_f32 v197, v59, v67
	v_pk_add_f32 v[32:33], v[64:65], v[32:33]
	v_mfma_f32_16x16x32_bf16 v[172:175], v[82:85], v[26:29], v[172:175]
	v_cvt_pk_bf16_f32 v198, v69, v53
	v_cvt_pk_bf16_f32 v199, v57, v61
	v_exp_f32_e32 v155, v7
	v_mfma_f32_16x16x32_bf16 v[2:5], v[78:81], v[26:29], v[2:5]
	v_mul_f32_e64 v28, v38, v34
	v_mul_f32_e64 v29, v39, v34
	v_pk_mul_f32 v[26:27], v[36:37], v[34:35] op_sel_hi:[1,0]
	v_sub_f32_e32 v7, v10, v113
	v_pk_add_f32 v[32:33], v[110:111], v[32:33]
	v_cvt_pk_bf16_f32 v6, v229, v230
	v_pk_mul_f32 v[18:19], v[18:19], v[34:35] op_sel_hi:[1,0]
	v_pk_mul_f32 v[16:17], v[16:17], v[34:35] op_sel_hi:[1,0]
	s_waitcnt lgkmcnt(6)
	v_mfma_f32_16x16x32_bf16 v[36:39], v[176:179], v[196:199], v[26:29]
	v_mul_f32_e64 v4, v4, v34
	v_mul_f32_e64 v5, v5, v34
	v_pk_mul_f32 v[2:3], v[2:3], v[34:35] op_sel_hi:[1,0]
	v_exp_f32_e32 v127, v7
	v_pk_mul_f32 v[28:29], v[174:175], v[34:35] op_sel_hi:[1,0]
	v_pk_mul_f32 v[26:27], v[172:173], v[34:35] op_sel_hi:[1,0]
	v_cvt_pk_bf16_f32 v7, v148, v130
	v_cvt_pk_bf16_f32 v8, v134, v138
	v_cvt_pk_bf16_f32 v9, v128, v132
	v_pk_add_f32 v[32:33], v[114:115], v[32:33]
	v_mov_b32_e32 v31, v1
	s_waitcnt lgkmcnt(3)
	v_mfma_f32_16x16x32_bf16 v[16:19], v[188:191], v[196:199], v[16:19]
	v_sub_f32_e32 v10, v11, v113
	v_sub_f32_e32 v116, v228, v113
	v_exp_f32_e32 v11, v10
	v_mfma_f32_16x16x32_bf16 v[172:175], v[180:183], v[196:199], v[26:29]
	v_exp_f32_e32 v10, v116
	ds_read_b128 v[208:211], v112 offset:45888
	v_cvt_pk_bf16_f32 v54, v149, v131
	v_mfma_f32_16x16x32_bf16 v[2:5], v[184:187], v[196:199], v[2:5]
	v_cvt_pk_bf16_f32 v198, v49, v21
	v_cvt_pk_bf16_f32 v196, v63, v65
	v_cvt_pk_bf16_f32 v197, v111, v115
	v_mfma_f32_16x16x32_bf16 v[40:43], v[98:101], v[6:9], v[42:45]
	v_cvt_pk_bf16_f32 v199, v47, v35
	v_cvt_pk_bf16_f32 v55, v135, v139
	v_cvt_pk_bf16_f32 v56, v129, v133
	v_pk_add_f32 v[44:45], v[48:49], v[32:33]
	v_pk_add_f32 v[48:49], v[148:149], v[30:31]
	s_waitcnt lgkmcnt(3)
	v_mfma_f32_16x16x32_bf16 v[26:29], v[192:195], v[196:199], v[16:19]
	v_add_f32_e64 v48, v130, v48
	v_add_f32_e64 v49, v131, v49
	v_cvt_pk_bf16_f32 v33, v127, v11
	v_pk_add_f32 v[48:49], v[134:135], v[48:49]
	s_waitcnt lgkmcnt(2)
	v_mfma_f32_16x16x32_bf16 v[16:19], v[200:203], v[196:199], v[36:39]
	v_add_f32_e64 v48, v138, v48
	v_add_f32_e64 v49, v139, v49
	v_cvt_pk_bf16_f32 v57, v137, v141
	v_pk_add_f32 v[48:49], v[128:129], v[48:49]
	v_mfma_f32_16x16x32_bf16 v[36:39], v[106:109], v[6:9], v[74:77]
	v_add_f32_e64 v48, v132, v48
	v_add_f32_e64 v49, v133, v49
	v_cvt_pk_bf16_f32 v30, v143, v145
	v_pk_add_f32 v[48:49], v[136:137], v[48:49]
	v_mfma_f32_16x16x32_bf16 v[70:73], v[102:105], v[6:9], v[70:73]
	v_add_f32_e64 v48, v140, v48
	v_add_f32_e64 v49, v141, v49
	v_cvt_pk_bf16_f32 v31, v147, v151
	v_pk_add_f32 v[48:49], v[142:143], v[48:49]
	v_mfma_f32_16x16x32_bf16 v[6:9], v[94:97], v[6:9], v[22:25]
	v_add_f32_e64 v48, v144, v48
	v_add_f32_e64 v49, v145, v49
	v_cvt_pk_bf16_f32 v32, v153, v155
	v_pk_add_f32 v[48:49], v[146:147], v[48:49]
	v_cvt_pk_bf16_f32 v22, v136, v140
	v_pk_add_f32 v[48:49], v[150:151], v[48:49]
	v_cvt_pk_bf16_f32 v23, v142, v144
	v_pk_add_f32 v[48:49], v[152:153], v[48:49]
	v_cvt_pk_bf16_f32 v24, v146, v150
	v_pk_add_f32 v[48:49], v[154:155], v[48:49]
	v_cvt_pk_bf16_f32 v25, v152, v154
	v_pk_add_f32 v[48:49], v[126:127], v[48:49]
	s_waitcnt lgkmcnt(0)
	v_add_f32_e32 v49, v49, v11
	v_mfma_f32_16x16x32_bf16 v[36:39], v[90:93], v[22:25], v[36:39]
	v_fmac_f32_e32 v49, v48, v10
	ds_bpermute_b32 v48, v165, v49
	s_barrier
	v_mfma_f32_16x16x32_bf16 v[50:53], v[86:89], v[22:25], v[70:73]
	s_waitcnt lgkmcnt(0)
	v_mfma_f32_16x16x32_bf16 v[40:43], v[82:85], v[22:25], v[40:43]
	v_mfma_f32_16x16x32_bf16 v[6:9], v[78:81], v[22:25], v[6:9]
	s_nop 0
	v_mul_f32_e64 v24, v38, v10
	v_mul_f32_e64 v25, v39, v10
	v_pk_mul_f32 v[22:23], v[36:37], v[10:11] op_sel_hi:[1,0]
	s_nop 0
	v_pk_mul_f32 v[38:39], v[52:53], v[10:11] op_sel_hi:[1,0]
	v_pk_mul_f32 v[36:37], v[50:51], v[10:11] op_sel_hi:[1,0]
	v_pk_mul_f32 v[42:43], v[42:43], v[10:11] op_sel_hi:[1,0]
	v_pk_mul_f32 v[40:41], v[40:41], v[10:11] op_sel_hi:[1,0]
	v_pk_mul_f32 v[8:9], v[8:9], v[10:11] op_sel_hi:[1,0]
	v_pk_mul_f32 v[6:7], v[6:7], v[10:11] op_sel_hi:[1,0]
	v_pk_add_f32 v[10:11], v[20:21], v[44:45]
	v_mfma_f32_16x16x32_bf16 v[22:25], v[188:191], v[54:57], v[22:25]
	v_add_f32_e64 v10, v46, v10
	v_add_f32_e64 v11, v47, v11
	v_add_f32_e32 v21, v11, v35
	v_add_f32_e32 v11, v49, v48
	ds_bpermute_b32 v20, v166, v11
	v_mfma_f32_16x16x32_bf16 v[36:39], v[176:179], v[54:57], v[36:39]
	v_fmac_f32_e32 v21, v10, v34
	s_waitcnt lgkmcnt(0)
	v_add_f32_e32 v20, v11, v20
	v_mfma_f32_16x16x32_bf16 v[40:43], v[180:183], v[54:57], v[40:43]
	v_lshl_add_u64 v[10:11], v[120:121], 0, v[0:1]
	v_mfma_f32_16x16x32_bf16 v[6:9], v[184:187], v[54:57], v[6:9]
	v_mfma_f32_16x16x32_bf16 v[22:25], v[192:195], v[30:33], v[22:25]
	v_mfma_f32_16x16x32_bf16 v[36:39], v[200:203], v[30:33], v[36:39]
	v_mfma_f32_16x16x32_bf16 v[40:43], v[204:207], v[30:33], v[40:43]
	v_mfma_f32_16x16x32_bf16 v[6:9], v[208:211], v[30:33], v[6:9]
	v_div_scale_f32 v30, s[2:3], v20, v20, 1.0
	v_rcp_f32_e32 v31, v30
	v_mfma_f32_16x16x32_bf16 v[12:15], v[204:207], v[196:199], v[172:175]
	v_fma_f32 v0, -v30, v31, 1.0
	v_fmac_f32_e32 v31, v0, v31
	v_div_scale_f32 v0, vcc, 1.0, v20, 1.0
	v_mul_f32_e32 v32, v0, v31
	v_fma_f32 v33, -v30, v32, v0
	v_fmac_f32_e32 v32, v33, v31
	v_fma_f32 v0, -v30, v32, v0
	v_div_fmas_f32 v0, v0, v31, v32
	v_mov_b64_e32 v[30:31], s[12:13]
	v_mad_u64_u32 v[30:31], s[2:3], v10, s33, v[30:31]
	v_div_fixup_f32 v20, v0, v20, 1.0
	v_mad_i32_i24 v31, v11, s33, v31
	v_lshlrev_b32_e32 v0, 1, v119
	v_mov_b32_e32 v119, v1
	v_lshl_add_u64 v[10:11], v[30:31], 0, v[0:1]
	v_lshl_add_u64 v[10:11], v[10:11], 0, v[118:119]
	s_mov_b64 s[2:3], 0xa000c00
	ds_bpermute_b32 v0, v165, v21
	v_lshl_add_u64 v[30:31], v[10:11], 0, s[2:3]
	v_pk_mul_f32 v[22:23], v[22:23], v[20:21] op_sel_hi:[1,0]
	v_pk_mul_f32 v[24:25], v[24:25], v[20:21] op_sel_hi:[1,0]
	s_mov_b32 s2, 0xa000000
	v_cvt_pk_bf16_f32 v22, v22, v23
	v_cvt_pk_bf16_f32 v23, v24, v25
	v_add_co_u32_e32 v24, vcc, s2, v10
	s_waitcnt lgkmcnt(0)
	v_add_f32_e32 v0, v21, v0
	v_addc_co_u32_e32 v25, vcc, 0, v11, vcc
	global_store_dwordx2 v[24:25], v[22:23], off offset:3072
	v_pk_mul_f32 v[22:23], v[36:37], v[20:21] op_sel_hi:[1,0]
	v_pk_mul_f32 v[24:25], v[38:39], v[20:21] op_sel_hi:[1,0]
	v_cvt_pk_bf16_f32 v22, v22, v23
	v_cvt_pk_bf16_f32 v23, v24, v25
	global_store_dwordx2 v[30:31], v[22:23], off offset:32
	v_pk_mul_f32 v[22:23], v[40:41], v[20:21] op_sel_hi:[1,0]
	v_pk_mul_f32 v[24:25], v[42:43], v[20:21] op_sel_hi:[1,0]
	ds_bpermute_b32 v21, v166, v0
	v_mfma_f32_16x16x32_bf16 v[2:5], v[208:211], v[196:199], v[2:5]
	v_cvt_pk_bf16_f32 v22, v22, v23
	v_cvt_pk_bf16_f32 v23, v24, v25
	global_store_dwordx2 v[30:31], v[22:23], off offset:64
	s_waitcnt lgkmcnt(0)
	v_add_f32_e32 v0, v0, v21
	v_pk_mul_f32 v[6:7], v[6:7], v[20:21] op_sel_hi:[1,0]
	v_pk_mul_f32 v[8:9], v[8:9], v[20:21] op_sel_hi:[1,0]
	v_div_scale_f32 v20, s[2:3], v0, v0, 1.0
	v_rcp_f32_e32 v21, v20
	v_cvt_pk_bf16_f32 v6, v6, v7
	v_cvt_pk_bf16_f32 v7, v8, v9
	global_store_dwordx2 v[30:31], v[6:7], off offset:96
	v_fma_f32 v6, -v20, v21, 1.0
	v_fmac_f32_e32 v21, v6, v21
	v_div_scale_f32 v6, vcc, 1.0, v0, 1.0
	v_mul_f32_e32 v7, v6, v21
	v_fma_f32 v8, -v20, v7, v6
	v_fmac_f32_e32 v7, v8, v21
	v_fma_f32 v6, -v20, v7, v6
	v_div_fmas_f32 v6, v6, v21, v7
	s_mov_b64 s[2:3], 0xa01e000
	v_div_fixup_f32 v0, v6, v0, 1.0
	v_lshl_add_u64 v[6:7], v[10:11], 0, s[2:3]
	s_mov_b32 s2, 0xa01e000
	v_pk_mul_f32 v[8:9], v[26:27], v[0:1] op_sel_hi:[1,0]
	v_pk_mul_f32 v[20:21], v[28:29], v[0:1] op_sel_hi:[1,0]
	v_add_co_u32_e32 v10, vcc, s2, v10
	v_cvt_pk_bf16_f32 v8, v8, v9
	v_cvt_pk_bf16_f32 v9, v20, v21
	v_addc_co_u32_e32 v11, vcc, 0, v11, vcc
	global_store_dwordx2 v[10:11], v[8:9], off
	v_pk_mul_f32 v[8:9], v[16:17], v[0:1] op_sel_hi:[1,0]
	v_pk_mul_f32 v[10:11], v[18:19], v[0:1] op_sel_hi:[1,0]
	v_cvt_pk_bf16_f32 v8, v8, v9
	v_cvt_pk_bf16_f32 v9, v10, v11
	global_store_dwordx2 v[6:7], v[8:9], off offset:32
	v_pk_mul_f32 v[8:9], v[12:13], v[0:1] op_sel_hi:[1,0]
	v_pk_mul_f32 v[10:11], v[14:15], v[0:1] op_sel_hi:[1,0]
	v_pk_mul_f32 v[2:3], v[2:3], v[0:1] op_sel_hi:[1,0]
	v_pk_mul_f32 v[4:5], v[4:5], v[0:1] op_sel_hi:[1,0]
	v_cvt_pk_bf16_f32 v8, v8, v9
	v_cvt_pk_bf16_f32 v9, v10, v11
	v_cvt_pk_bf16_f32 v2, v2, v3
	v_cvt_pk_bf16_f32 v3, v4, v5
	global_store_dwordx2 v[6:7], v[8:9], off offset:64
	global_store_dwordx2 v[6:7], v[2:3], off offset:96
